# v5 + first K-loop iteration peeled with C=0 (accumulator zeroing removed) in 6 multi-round GEMM phases + residual-add epilogue loads de-serialised in 5 phases
# speedup vs baseline: 1.0074x; 1.0074x over previous
; #define PG8_STAGE(bufoff, gbase, voff) do { _Pragma("unroll") for (int _i = 0; _i < 2; ++_i) \
;         __builtin_amdgcn_global_load_lds((const unsigned*)((const char*)(gbase) + (voff)[_i]), (PG8_LAS unsigned*)(lds + (bufoff) + ldsw + _i * 8192), 16, 0, 0); } while (0)
; #define PG8_LDA(dst, b, h) do { _Pragma("unroll") for (int m = 0; m < 4; ++m) _Pragma("unroll") for (int k = 0; k < 2; ++k) dst[m][k] = *(const PG8_LAS bf16x8*)(lds + PG8_SA(b, h) + aoff + m * 2048 + k * 1024); } while (0)
; #define PG8_LDB(dst, b, h) do { _Pragma("unroll") for (int n = 0; n < 2; ++n) _Pragma("unroll") for (int k = 0; k < 2; ++k) dst[n][k] = *(const PG8_LAS bf16x8*)(lds + PG8_SB(b, h) + boff + n * 2048 + k * 1024); } while (0)
; #define PG8_WAIT_V(n) asm volatile("s_waitcnt vmcnt(" #n ")" ::: "memory")
; #define PG8_WAIT_L(n) asm volatile("s_waitcnt lgkmcnt(" #n ")" ::: "memory")
; #define PG8_BAR __builtin_amdgcn_s_barrier()
; #define PG8_SCHED __builtin_amdgcn_sched_barrier(0)
; template <class Epi, class Sched, bool ALIGN_EPI = false, bool SP2 = false, bool F16 = false, bool TOKPERM = false>
; __device__ __forceinline__ void gemm_phase(PG8_LAS unsigned char* lds, const Gemm g, const Sched& S, const Epi& E, int wv) {
;     ...
;         const bool has_next = S.next(ui + 1, nxt);
;         const char* nA = has_next ? (const char*)g.A + (size_t)nxt.pm * tstep : cA; const char* nB = has_next ? (const char*)g.Bt + (size_t)nxt.pn * tstep : cB;
;         for (int t = 0; t < nt; t += 2) {
;             const bool last = (t == nt - 2);
;             const char* a1 = cA + (size_t)(t + 1) * kstep;
;             const char* a2 = last ? nA : cA + (size_t)(t + 2) * kstep; const char* b2 = last ? nB : cB + (size_t)(t + 2) * kstep;
;             const char* a3 = a2 + kstep; const char* b3 = b2 + kstep;
;             if (last && has_next) S.a_ready(nxt);
;             if constexpr (SP2) {
;             PG8_LDB(B0, 0, 0); PG8_LDB(B1, 0, 1); PG8_SCHED; PG8_LDA(At, 0, 0); PG8_STAGE(PG8_SA(1, 1), a1 + hstep, voffA);
;             PG8_WAIT_V(8); PG8_WAIT_L(0); PG8_BAR; PG8_MMA(0, 0, At, B0); PG8_MMA(0, 1, At, B1); PG8_BAR; PG8_SCHED;
;             PG8_LDA(At, 0, 1); PG8_STAGE(PG8_SB(0, 0), b2, voffB); PG8_STAGE(PG8_SB(0, 1), b2 + hstep, voffB); PG8_STAGE(PG8_SA(0, 0), a2, voffA);
;             PG8_WAIT_V(8); PG8_WAIT_L(0); PG8_BAR; PG8_MMA(1, 0, At, B0); PG8_MMA(1, 1, At, B1); PG8_BAR; PG8_SCHED;
.LBB0_180:
	s_ashr_i32 s51, s50, 31
	s_lshl_b64 s[52:53], s[50:51], 19
	s_add_u32 s52, s40, s52
	s_addc_u32 s53, s41, s53
	s_and_b64 s[54:55], s[2:3], exec
	s_cselect_b32 s51, s53, s7
	s_cselect_b32 s77, s52, s6
	s_ashr_i32 s49, s48, 31
	s_lshl_b64 s[54:55], s[48:49], 19
	s_add_u32 s54, s33, s54
	s_addc_u32 s55, s36, s55
	s_and_b64 s[56:57], s[2:3], exec
	s_cselect_b32 s49, s55, s9
	s_cselect_b32 s78, s54, s8
	s_add_u32 s6, s6, 0x40080
	s_addc_u32 s7, s7, 0
	s_add_u32 s79, s8, 0x100
	s_addc_u32 s80, s9, 0
	s_mov_b32 s81, -2
	ds_read_b128 v[172:175], v155
	ds_read_b128 v[176:179], v156
	ds_read_b128 v[180:183], v157
	ds_read_b128 v[184:187], v158
	ds_read_b128 v[188:191], v159
	ds_read_b128 v[192:195], v160
	ds_read_b128 v[196:199], v161
	ds_read_b128 v[200:203], v162
	s_add_u32 s8, s6, 0xfffc0080
	s_addc_u32 s9, s7, -1
	s_cmp_eq_u32 s81, 12
	s_cselect_b32 s57, s51, s9
	s_cselect_b32 s56, s77, s8
	s_cselect_b32 s9, s49, s80
	s_cselect_b32 s8, s78, s79
	s_mov_b32 m0, s73
	v_lshl_add_u64 v[148:149], s[6:7], 0, v[140:141]
	ds_read_b128 v[204:207], v153
	ds_read_b128 v[208:211], v153 offset:1024
	ds_read_b128 v[212:215], v153 offset:2048
	ds_read_b128 v[216:219], v153 offset:3072
	ds_read_b128 v[220:223], v153 offset:4096
	ds_read_b128 v[228:231], v153 offset:5120
	ds_read_b128 v[232:235], v153 offset:6144
	ds_read_b128 v[236:239], v153 offset:7168
	global_load_lds_dwordx4 v[148:149], off
	v_lshl_add_u64 v[148:149], s[6:7], 0, v[142:143]
	s_mov_b32 m0, s74
	s_nop 0
	global_load_lds_dwordx4 v[148:149], off
	s_waitcnt vmcnt(8)
	s_waitcnt lgkmcnt(0)
	s_barrier
	s_setprio 1
	s_waitcnt lgkmcnt(0)
	v_mfma_f32_16x16x32_f16 v[124:127], v[172:175], v[204:207], 0
	v_mfma_f32_16x16x32_f16 v[116:119], v[180:183], v[204:207], 0
	v_mfma_f32_16x16x32_f16 v[108:111], v[172:175], v[212:215], 0
	v_mfma_f32_16x16x32_f16 v[104:107], v[180:183], v[212:215], 0
	v_mfma_f32_16x16x32_f16 v[92:95], v[172:175], v[220:223], 0
	v_mfma_f32_16x16x32_f16 v[88:91], v[180:183], v[220:223], 0
	v_mfma_f32_16x16x32_f16 v[76:79], v[172:175], v[232:235], 0
	v_mfma_f32_16x16x32_f16 v[72:75], v[180:183], v[232:235], 0
	v_mfma_f32_16x16x32_f16 v[124:127], v[176:179], v[208:211], v[124:127]
	v_mfma_f32_16x16x32_f16 v[116:119], v[184:187], v[208:211], v[116:119]
	v_mfma_f32_16x16x32_f16 v[108:111], v[176:179], v[216:219], v[108:111]
	v_mfma_f32_16x16x32_f16 v[104:107], v[184:187], v[216:219], v[104:107]
	v_mfma_f32_16x16x32_f16 v[92:95], v[176:179], v[228:231], v[92:95]
	v_mfma_f32_16x16x32_f16 v[88:91], v[184:187], v[228:231], v[88:91]
	v_mfma_f32_16x16x32_f16 v[76:79], v[176:179], v[236:239], v[76:79]
	v_mfma_f32_16x16x32_f16 v[72:75], v[184:187], v[236:239], v[72:75]
	s_setprio 0
	s_setprio 1
	v_mfma_f32_16x16x32_f16 v[120:123], v[188:191], v[204:207], 0
	v_mfma_f32_16x16x32_f16 v[112:115], v[196:199], v[204:207], 0
	v_mfma_f32_16x16x32_f16 v[100:103], v[188:191], v[212:215], 0
	v_mfma_f32_16x16x32_f16 v[96:99], v[196:199], v[212:215], 0
	v_mfma_f32_16x16x32_f16 v[84:87], v[188:191], v[220:223], 0
	v_mfma_f32_16x16x32_f16 v[80:83], v[196:199], v[220:223], 0
	v_mfma_f32_16x16x32_f16 v[68:71], v[188:191], v[232:235], 0
	v_mfma_f32_16x16x32_f16 v[64:67], v[196:199], v[232:235], 0
	v_mfma_f32_16x16x32_f16 v[120:123], v[192:195], v[208:211], v[120:123]
	v_mfma_f32_16x16x32_f16 v[112:115], v[200:203], v[208:211], v[112:115]
	v_mfma_f32_16x16x32_f16 v[100:103], v[192:195], v[216:219], v[100:103]
	v_mfma_f32_16x16x32_f16 v[96:99], v[200:203], v[216:219], v[96:99]
	v_mfma_f32_16x16x32_f16 v[84:87], v[192:195], v[228:231], v[84:87]
	v_mfma_f32_16x16x32_f16 v[80:83], v[200:203], v[228:231], v[80:83]
	v_mfma_f32_16x16x32_f16 v[68:71], v[192:195], v[236:239], v[68:71]
	v_mfma_f32_16x16x32_f16 v[64:67], v[200:203], v[236:239], v[64:67]
	s_setprio 0
	s_barrier
	s_mov_b32 m0, s37
	v_lshl_add_u64 v[148:149], s[8:9], 0, v[132:133]
	s_add_u32 s82, s8, 0x40000
	ds_read_b128 v[204:207], v153 offset:16384
	ds_read_b128 v[208:211], v153 offset:17408
	ds_read_b128 v[212:215], v153 offset:18432
	ds_read_b128 v[216:219], v153 offset:19456
	ds_read_b128 v[220:223], v153 offset:20480
	ds_read_b128 v[228:231], v153 offset:21504
	ds_read_b128 v[232:235], v153 offset:22528
	ds_read_b128 v[236:239], v153 offset:23552
	global_load_lds_dwordx4 v[148:149], off
	v_lshl_add_u64 v[224:225], s[8:9], 0, v[128:129]
	s_mov_b32 m0, s45
	s_addc_u32 s83, s9, 0
	global_load_lds_dwordx4 v[224:225], off
	v_lshl_add_u64 v[240:241], s[82:83], 0, v[132:133]
	s_mov_b32 m0, s58
	v_lshl_add_u64 v[242:243], s[56:57], 0, v[130:131]
	global_load_lds_dwordx4 v[240:241], off
	v_lshl_add_u64 v[240:241], s[82:83], 0, v[128:129]
	s_mov_b32 m0, s59
	s_nop 0
	global_load_lds_dwordx4 v[240:241], off
	v_lshl_add_u64 v[240:241], s[56:57], 0, v[134:135]
	s_mov_b32 m0, s20
	s_nop 0
	global_load_lds_dwordx4 v[240:241], off
	s_mov_b32 m0, s60
	s_nop 0
	global_load_lds_dwordx4 v[242:243], off
	s_waitcnt vmcnt(8)
	s_waitcnt lgkmcnt(0)
	s_barrier
; #define PG8_STAGE(bufoff, gbase, voff) do { _Pragma("unroll") for (int _i = 0; _i < 2; ++_i) \
;         __builtin_amdgcn_global_load_lds((const unsigned*)((const char*)(gbase) + (voff)[_i]), (PG8_LAS unsigned*)(lds + (bufoff) + ldsw + _i * 8192), 16, 0, 0); } while (0)
; #define PG8_LDA(dst, b, h) do { _Pragma("unroll") for (int m = 0; m < 4; ++m) _Pragma("unroll") for (int k = 0; k < 2; ++k) dst[m][k] = *(const PG8_LAS bf16x8*)(lds + PG8_SA(b, h) + aoff + m * 2048 + k * 1024); } while (0)
; #define PG8_LDB(dst, b, h) do { _Pragma("unroll") for (int n = 0; n < 2; ++n) _Pragma("unroll") for (int k = 0; k < 2; ++k) dst[n][k] = *(const PG8_LAS bf16x8*)(lds + PG8_SB(b, h) + boff + n * 2048 + k * 1024); } while (0)
; #define PG8_MMA(ai, bj, At, Bt) do { __builtin_amdgcn_s_setprio(1); _Pragma("unroll") for (int m = 0; m < 4; ++m) _Pragma("unroll") for (int n = 0; n < 2; ++n) _Pragma("unroll") for (int k = 0; k < 2; ++k) \
;         acc[ai][bj][m][n] = mma16<F16>(Bt[n][k], At[m][k], acc[ai][bj][m][n]); __builtin_amdgcn_s_setprio(0); } while (0)
; #define PG8_WAIT_V(n) asm volatile("s_waitcnt vmcnt(" #n ")" ::: "memory")
; #define PG8_WAIT_L(n) asm volatile("s_waitcnt lgkmcnt(" #n ")" ::: "memory")
; #define PG8_BAR __builtin_amdgcn_s_barrier()
; #define PG8_SCHED __builtin_amdgcn_sched_barrier(0)
; template <class Epi, class Sched, bool ALIGN_EPI = false, bool SP2 = false, bool F16 = false, bool TOKPERM = false>
; __device__ __forceinline__ void gemm_phase(PG8_LAS unsigned char* lds, const Gemm g, const Sched& S, const Epi& E, int wv) {
;     ...
;             PG8_WAIT_V(8); PG8_WAIT_L(0); PG8_BAR; PG8_MMA(1, 0, At, B0); PG8_MMA(1, 1, At, B1); PG8_BAR; PG8_SCHED;
;             PG8_LDB(B0, 1, 0); PG8_LDB(B1, 1, 1); PG8_SCHED; PG8_LDA(At, 1, 0); PG8_STAGE(PG8_SA(0, 1), a2 + hstep, voffA);
;             PG8_WAIT_V(8); PG8_WAIT_L(0); PG8_BAR; PG8_MMA(0, 0, At, B0); PG8_MMA(0, 1, At, B1); PG8_BAR; PG8_SCHED;
	s_setprio 1
	s_waitcnt lgkmcnt(0)
	v_mfma_f32_16x16x32_f16 v[60:63], v[172:175], v[204:207], 0
	v_mfma_f32_16x16x32_f16 v[56:59], v[180:183], v[204:207], 0
	v_mfma_f32_16x16x32_f16 v[44:47], v[172:175], v[212:215], 0
	v_mfma_f32_16x16x32_f16 v[40:43], v[180:183], v[212:215], 0
	v_mfma_f32_16x16x32_f16 v[28:31], v[172:175], v[220:223], 0
	v_mfma_f32_16x16x32_f16 v[24:27], v[180:183], v[220:223], 0
	v_mfma_f32_16x16x32_f16 v[12:15], v[172:175], v[232:235], 0
	v_mfma_f32_16x16x32_f16 v[8:11], v[180:183], v[232:235], 0
	v_mfma_f32_16x16x32_f16 v[60:63], v[176:179], v[208:211], v[60:63]
	v_mfma_f32_16x16x32_f16 v[56:59], v[184:187], v[208:211], v[56:59]
	v_mfma_f32_16x16x32_f16 v[44:47], v[176:179], v[216:219], v[44:47]
	v_mfma_f32_16x16x32_f16 v[40:43], v[184:187], v[216:219], v[40:43]
	v_mfma_f32_16x16x32_f16 v[28:31], v[176:179], v[228:231], v[28:31]
	v_mfma_f32_16x16x32_f16 v[24:27], v[184:187], v[228:231], v[24:27]
	v_mfma_f32_16x16x32_f16 v[12:15], v[176:179], v[236:239], v[12:15]
	v_mfma_f32_16x16x32_f16 v[8:11], v[184:187], v[236:239], v[8:11]
	s_setprio 0
	s_setprio 1
	v_mfma_f32_16x16x32_f16 v[52:55], v[188:191], v[204:207], 0
	v_mfma_f32_16x16x32_f16 v[48:51], v[196:199], v[204:207], 0
	v_mfma_f32_16x16x32_f16 v[36:39], v[188:191], v[212:215], 0
	v_mfma_f32_16x16x32_f16 v[32:35], v[196:199], v[212:215], 0
	v_mfma_f32_16x16x32_f16 v[20:23], v[188:191], v[220:223], 0
	v_mfma_f32_16x16x32_f16 v[16:19], v[196:199], v[220:223], 0
	v_mfma_f32_16x16x32_f16 v[4:7], v[188:191], v[232:235], 0
	v_mfma_f32_16x16x32_f16 v[0:3], v[196:199], v[232:235], 0
	v_mfma_f32_16x16x32_f16 v[52:55], v[192:195], v[208:211], v[52:55]
	v_mfma_f32_16x16x32_f16 v[48:51], v[200:203], v[208:211], v[48:51]
	v_mfma_f32_16x16x32_f16 v[36:39], v[192:195], v[216:219], v[36:39]
	v_mfma_f32_16x16x32_f16 v[32:35], v[200:203], v[216:219], v[32:35]
	v_mfma_f32_16x16x32_f16 v[20:23], v[192:195], v[228:231], v[20:23]
	v_mfma_f32_16x16x32_f16 v[16:19], v[200:203], v[228:231], v[16:19]
	v_mfma_f32_16x16x32_f16 v[4:7], v[192:195], v[236:239], v[4:7]
	v_mfma_f32_16x16x32_f16 v[0:3], v[200:203], v[236:239], v[0:3]
	s_setprio 0
	s_barrier
	ds_read_b128 v[172:175], v163
	ds_read_b128 v[176:179], v164
	ds_read_b128 v[180:183], v165
	ds_read_b128 v[184:187], v166
	ds_read_b128 v[188:191], v167
	ds_read_b128 v[192:195], v168
	ds_read_b128 v[196:199], v169
	ds_read_b128 v[200:203], v170
	s_add_u32 s56, s56, 0x40000
	s_addc_u32 s57, s57, 0
	s_mov_b32 m0, s61
	v_lshl_add_u64 v[244:245], s[56:57], 0, v[134:135]
	ds_read_b128 v[204:207], v153 offset:32768
	ds_read_b128 v[208:211], v153 offset:33792
	ds_read_b128 v[212:215], v153 offset:34816
	ds_read_b128 v[216:219], v153 offset:35840
	ds_read_b128 v[220:223], v153 offset:36864
	ds_read_b128 v[228:231], v153 offset:37888
	ds_read_b128 v[232:235], v153 offset:38912
	ds_read_b128 v[236:239], v153 offset:39936
	global_load_lds_dwordx4 v[244:245], off
	v_lshl_add_u64 v[244:245], s[56:57], 0, v[130:131]
	s_mov_b32 m0, s62
	s_nop 0
	global_load_lds_dwordx4 v[244:245], off
	s_waitcnt vmcnt(8)
	s_waitcnt lgkmcnt(0)
	s_barrier
	s_setprio 1
	s_waitcnt lgkmcnt(0)
	v_mfma_f32_16x16x32_f16 v[124:127], v[172:175], v[204:207], v[124:127]
	v_mfma_f32_16x16x32_f16 v[116:119], v[180:183], v[204:207], v[116:119]
	v_mfma_f32_16x16x32_f16 v[108:111], v[172:175], v[212:215], v[108:111]
	v_mfma_f32_16x16x32_f16 v[104:107], v[180:183], v[212:215], v[104:107]
	v_mfma_f32_16x16x32_f16 v[92:95], v[172:175], v[220:223], v[92:95]
	v_mfma_f32_16x16x32_f16 v[88:91], v[180:183], v[220:223], v[88:91]
	v_mfma_f32_16x16x32_f16 v[76:79], v[172:175], v[232:235], v[76:79]
	v_mfma_f32_16x16x32_f16 v[72:75], v[180:183], v[232:235], v[72:75]
	v_mfma_f32_16x16x32_f16 v[124:127], v[176:179], v[208:211], v[124:127]
	v_mfma_f32_16x16x32_f16 v[116:119], v[184:187], v[208:211], v[116:119]
	v_mfma_f32_16x16x32_f16 v[108:111], v[176:179], v[216:219], v[108:111]
	v_mfma_f32_16x16x32_f16 v[104:107], v[184:187], v[216:219], v[104:107]
	v_mfma_f32_16x16x32_f16 v[92:95], v[176:179], v[228:231], v[92:95]
	v_mfma_f32_16x16x32_f16 v[88:91], v[184:187], v[228:231], v[88:91]
	v_mfma_f32_16x16x32_f16 v[76:79], v[176:179], v[236:239], v[76:79]
	v_mfma_f32_16x16x32_f16 v[72:75], v[184:187], v[236:239], v[72:75]
	s_setprio 0
	s_setprio 1
	v_mfma_f32_16x16x32_f16 v[120:123], v[188:191], v[204:207], v[120:123]
	v_mfma_f32_16x16x32_f16 v[112:115], v[196:199], v[204:207], v[112:115]
	v_mfma_f32_16x16x32_f16 v[100:103], v[188:191], v[212:215], v[100:103]
	v_mfma_f32_16x16x32_f16 v[96:99], v[196:199], v[212:215], v[96:99]
	v_mfma_f32_16x16x32_f16 v[84:87], v[188:191], v[220:223], v[84:87]
	v_mfma_f32_16x16x32_f16 v[80:83], v[196:199], v[220:223], v[80:83]
	v_mfma_f32_16x16x32_f16 v[68:71], v[188:191], v[232:235], v[68:71]
	v_mfma_f32_16x16x32_f16 v[64:67], v[196:199], v[232:235], v[64:67]
	v_mfma_f32_16x16x32_f16 v[120:123], v[192:195], v[208:211], v[120:123]
	v_mfma_f32_16x16x32_f16 v[112:115], v[200:203], v[208:211], v[112:115]
	v_mfma_f32_16x16x32_f16 v[100:103], v[192:195], v[216:219], v[100:103]
	v_mfma_f32_16x16x32_f16 v[96:99], v[200:203], v[216:219], v[96:99]
	v_mfma_f32_16x16x32_f16 v[84:87], v[192:195], v[228:231], v[84:87]
	v_mfma_f32_16x16x32_f16 v[80:83], v[200:203], v[228:231], v[80:83]
	v_mfma_f32_16x16x32_f16 v[68:71], v[192:195], v[236:239], v[68:71]
	v_mfma_f32_16x16x32_f16 v[64:67], v[200:203], v[236:239], v[64:67]
	s_setprio 0
	s_barrier
; #define PG8_STAGE(bufoff, gbase, voff) do { _Pragma("unroll") for (int _i = 0; _i < 2; ++_i) \
;         __builtin_amdgcn_global_load_lds((const unsigned*)((const char*)(gbase) + (voff)[_i]), (PG8_LAS unsigned*)(lds + (bufoff) + ldsw + _i * 8192), 16, 0, 0); } while (0)
; #define PG8_LDA(dst, b, h) do { _Pragma("unroll") for (int m = 0; m < 4; ++m) _Pragma("unroll") for (int k = 0; k < 2; ++k) dst[m][k] = *(const PG8_LAS bf16x8*)(lds + PG8_SA(b, h) + aoff + m * 2048 + k * 1024); } while (0)
; #define PG8_MMA(ai, bj, At, Bt) do { __builtin_amdgcn_s_setprio(1); _Pragma("unroll") for (int m = 0; m < 4; ++m) _Pragma("unroll") for (int n = 0; n < 2; ++n) _Pragma("unroll") for (int k = 0; k < 2; ++k) \
;         acc[ai][bj][m][n] = mma16<F16>(Bt[n][k], At[m][k], acc[ai][bj][m][n]); __builtin_amdgcn_s_setprio(0); } while (0)
; #define PG8_WAIT_V(n) asm volatile("s_waitcnt vmcnt(" #n ")" ::: "memory")
; #define PG8_WAIT_L(n) asm volatile("s_waitcnt lgkmcnt(" #n ")" ::: "memory")
; #define PG8_BAR __builtin_amdgcn_s_barrier()
; #define PG8_SCHED __builtin_amdgcn_sched_barrier(0)
; template <class Epi, class Sched, bool ALIGN_EPI = false, bool SP2 = false, bool F16 = false, bool TOKPERM = false>
; __device__ __forceinline__ void gemm_phase(PG8_LAS unsigned char* lds, const Gemm g, const Sched& S, const Epi& E, int wv) {
;     ...
;             PG8_LDA(At, 1, 1); PG8_STAGE(PG8_SB(1, 0), b3, voffB); PG8_STAGE(PG8_SB(1, 1), b3 + hstep, voffB); PG8_STAGE(PG8_SA(1, 0), a3, voffA);
;             PG8_WAIT_V(8); PG8_WAIT_L(0); PG8_BAR; PG8_MMA(1, 0, At, B0); PG8_MMA(1, 1, At, B1); PG8_BAR; PG8_SCHED;
	s_mov_b32 m0, s64
	v_lshl_add_u64 v[148:149], v[148:149], 0, s[16:17]
	s_add_u32 s8, s8, 0x40080
	ds_read_b128 v[204:207], v153 offset:49152
	ds_read_b128 v[208:211], v153 offset:50176
	ds_read_b128 v[212:215], v153 offset:51200
	ds_read_b128 v[216:219], v153 offset:52224
	ds_read_b128 v[220:223], v153 offset:53248
	ds_read_b128 v[228:231], v153 offset:54272
	ds_read_b128 v[232:235], v153 offset:55296
	ds_read_b128 v[236:239], v153 offset:56320
	global_load_lds_dwordx4 v[148:149], off
	v_lshl_add_u64 v[148:149], v[224:225], 0, s[16:17]
	s_mov_b32 m0, s65
	s_addc_u32 s9, s9, 0
	global_load_lds_dwordx4 v[148:149], off
	v_lshl_add_u64 v[148:149], s[8:9], 0, v[132:133]
	s_mov_b32 m0, s69
	s_nop 0
	global_load_lds_dwordx4 v[148:149], off
	v_lshl_add_u64 v[148:149], s[8:9], 0, v[128:129]
	s_mov_b32 m0, s70
	s_nop 0
	global_load_lds_dwordx4 v[148:149], off
	v_lshl_add_u64 v[148:149], v[240:241], 0, s[16:17]
	s_mov_b32 m0, s66
	s_nop 0
	global_load_lds_dwordx4 v[148:149], off
	v_lshl_add_u64 v[148:149], v[242:243], 0, s[16:17]
	s_mov_b32 m0, s68
	s_nop 0
	global_load_lds_dwordx4 v[148:149], off
	s_waitcnt vmcnt(8)
	s_waitcnt lgkmcnt(0)
	s_barrier
	s_setprio 1
	s_waitcnt lgkmcnt(0)
	v_mfma_f32_16x16x32_f16 v[60:63], v[172:175], v[204:207], v[60:63]
	v_mfma_f32_16x16x32_f16 v[56:59], v[180:183], v[204:207], v[56:59]
	v_mfma_f32_16x16x32_f16 v[44:47], v[172:175], v[212:215], v[44:47]
	v_mfma_f32_16x16x32_f16 v[40:43], v[180:183], v[212:215], v[40:43]
	v_mfma_f32_16x16x32_f16 v[28:31], v[172:175], v[220:223], v[28:31]
	v_mfma_f32_16x16x32_f16 v[24:27], v[180:183], v[220:223], v[24:27]
	v_mfma_f32_16x16x32_f16 v[12:15], v[172:175], v[232:235], v[12:15]
	v_mfma_f32_16x16x32_f16 v[8:11], v[180:183], v[232:235], v[8:11]
	v_mfma_f32_16x16x32_f16 v[60:63], v[176:179], v[208:211], v[60:63]
	v_mfma_f32_16x16x32_f16 v[56:59], v[184:187], v[208:211], v[56:59]
	v_mfma_f32_16x16x32_f16 v[44:47], v[176:179], v[216:219], v[44:47]
	v_mfma_f32_16x16x32_f16 v[40:43], v[184:187], v[216:219], v[40:43]
	v_mfma_f32_16x16x32_f16 v[28:31], v[176:179], v[228:231], v[28:31]
	v_mfma_f32_16x16x32_f16 v[24:27], v[184:187], v[228:231], v[24:27]
	v_mfma_f32_16x16x32_f16 v[12:15], v[176:179], v[236:239], v[12:15]
	v_mfma_f32_16x16x32_f16 v[8:11], v[184:187], v[236:239], v[8:11]
	s_setprio 0
	s_setprio 1
	v_mfma_f32_16x16x32_f16 v[52:55], v[188:191], v[204:207], v[52:55]
	v_mfma_f32_16x16x32_f16 v[48:51], v[196:199], v[204:207], v[48:51]
	v_mfma_f32_16x16x32_f16 v[36:39], v[188:191], v[212:215], v[36:39]
	v_mfma_f32_16x16x32_f16 v[32:35], v[196:199], v[212:215], v[32:35]
	v_mfma_f32_16x16x32_f16 v[20:23], v[188:191], v[220:223], v[20:23]
	v_mfma_f32_16x16x32_f16 v[16:19], v[196:199], v[220:223], v[16:19]
	v_mfma_f32_16x16x32_f16 v[4:7], v[188:191], v[232:235], v[4:7]
	v_mfma_f32_16x16x32_f16 v[0:3], v[196:199], v[232:235], v[0:3]
	v_mfma_f32_16x16x32_f16 v[52:55], v[192:195], v[208:211], v[52:55]
	v_mfma_f32_16x16x32_f16 v[48:51], v[200:203], v[208:211], v[48:51]
	v_mfma_f32_16x16x32_f16 v[36:39], v[192:195], v[216:219], v[36:39]
	v_mfma_f32_16x16x32_f16 v[32:35], v[200:203], v[216:219], v[32:35]
	v_mfma_f32_16x16x32_f16 v[20:23], v[192:195], v[228:231], v[20:23]
	v_mfma_f32_16x16x32_f16 v[16:19], v[200:203], v[228:231], v[16:19]
	v_mfma_f32_16x16x32_f16 v[4:7], v[192:195], v[236:239], v[4:7]
	v_mfma_f32_16x16x32_f16 v[0:3], v[200:203], v[236:239], v[0:3]
	s_setprio 0
	s_barrier
	s_add_i32 s81, s81, 2
	s_add_u32 s6, s6, 0x100
	s_addc_u32 s7, s7, 0
	s_add_u32 s79, s79, 0x100
	s_addc_u32 s80, s80, 0
	s_cmp_gt_u32 s81, 13

; #define PG8_STAGE(bufoff, gbase, voff) do { _Pragma("unroll") for (int _i = 0; _i < 2; ++_i) \
;         __builtin_amdgcn_global_load_lds((const unsigned*)((const char*)(gbase) + (voff)[_i]), (PG8_LAS unsigned*)(lds + (bufoff) + ldsw + _i * 8192), 16, 0, 0); } while (0)
; #define PG8_LDA(dst, b, h) do { _Pragma("unroll") for (int m = 0; m < 4; ++m) _Pragma("unroll") for (int k = 0; k < 2; ++k) dst[m][k] = *(const PG8_LAS bf16x8*)(lds + PG8_SA(b, h) + aoff + m * 2048 + k * 1024); } while (0)
; #define PG8_LDB(dst, b, h) do { _Pragma("unroll") for (int n = 0; n < 2; ++n) _Pragma("unroll") for (int k = 0; k < 2; ++k) dst[n][k] = *(const PG8_LAS bf16x8*)(lds + PG8_SB(b, h) + boff + n * 2048 + k * 1024); } while (0)
; #define PG8_WAIT_V(n) asm volatile("s_waitcnt vmcnt(" #n ")" ::: "memory")
; #define PG8_WAIT_L(n) asm volatile("s_waitcnt lgkmcnt(" #n ")" ::: "memory")
; #define PG8_BAR __builtin_amdgcn_s_barrier()
; #define PG8_SCHED __builtin_amdgcn_sched_barrier(0)
; template <class Epi, class Sched, bool ALIGN_EPI = false, bool SP2 = false, bool F16 = false, bool TOKPERM = false>
; __device__ __forceinline__ void gemm_phase(PG8_LAS unsigned char* lds, const Gemm g, const Sched& S, const Epi& E, int wv) {
;     ...
;         const bool has_next = S.next(ui + 1, nxt);
;         const char* nA = has_next ? (const char*)g.A + (size_t)nxt.pm * tstep : cA; const char* nB = has_next ? (const char*)g.Bt + (size_t)nxt.pn * tstep : cB;
;         for (int t = 0; t < nt; t += 2) {
;             const bool last = (t == nt - 2);
;             const char* a1 = cA + (size_t)(t + 1) * kstep;
;             const char* a2 = last ? nA : cA + (size_t)(t + 2) * kstep; const char* b2 = last ? nB : cB + (size_t)(t + 2) * kstep;
;             const char* a3 = a2 + kstep; const char* b3 = b2 + kstep;
;             if (last && has_next) S.a_ready(nxt);
;             if constexpr (SP2) {
;             PG8_LDB(B0, 0, 0); PG8_LDB(B1, 0, 1); PG8_SCHED; PG8_LDA(At, 0, 0); PG8_STAGE(PG8_SA(1, 1), a1 + hstep, voffA);
;             PG8_WAIT_V(8); PG8_WAIT_L(0); PG8_BAR; PG8_MMA(0, 0, At, B0); PG8_MMA(0, 1, At, B1); PG8_BAR; PG8_SCHED;
;             PG8_LDA(At, 0, 1); PG8_STAGE(PG8_SB(0, 0), b2, voffB); PG8_STAGE(PG8_SB(0, 1), b2 + hstep, voffB); PG8_STAGE(PG8_SA(0, 0), a2, voffA);
;             PG8_WAIT_V(8); PG8_WAIT_L(0); PG8_BAR; PG8_MMA(1, 0, At, B0); PG8_MMA(1, 1, At, B1); PG8_BAR; PG8_SCHED;
.LBB0_381:
	s_ashr_i32 s71, s70, 31
	s_lshl_b64 s[10:11], s[70:71], 19
	s_add_u32 s72, s40, s10
	s_addc_u32 s73, s41, s11
	s_and_b64 s[10:11], s[4:5], exec
	s_cselect_b32 s12, s73, s7
	s_cselect_b32 s13, s72, s6
	s_ashr_i32 s69, s68, 31
	s_lshl_b64 s[10:11], s[68:69], 19
	s_add_u32 s74, s46, s10
	s_addc_u32 s75, s47, s11
	s_and_b64 s[10:11], s[4:5], exec
	s_cselect_b32 s59, s75, s9
	s_cselect_b32 s64, s74, s8
	s_add_u32 s6, s6, 0x40080
	s_addc_u32 s7, s7, 0
	s_add_u32 s69, s8, 0x100
	s_addc_u32 s71, s9, 0
	s_mov_b32 s76, -2
	s_waitcnt lgkmcnt(0)
	ds_read_b128 v[156:159], v181
	ds_read_b128 v[160:163], v182
	ds_read_b128 v[164:167], v183
	ds_read_b128 v[168:171], v184
	ds_read_b128 v[172:175], v185
	ds_read_b128 v[176:179], v186
	ds_read_b128 v[200:203], v187
	ds_read_b128 v[204:207], v188
	s_add_u32 s8, s6, 0xfffc0080
	s_addc_u32 s9, s7, -1
	s_cmp_eq_u32 s76, 12
	s_cselect_b32 s11, s12, s9
	s_cselect_b32 s10, s13, s8
	s_cselect_b32 s9, s59, s71
	s_cselect_b32 s8, s64, s69
	s_mov_b32 m0, s36
	v_lshl_add_u64 v[224:225], s[6:7], 0, v[146:147]
	ds_read_b128 v[208:211], v155
	ds_read_b128 v[212:215], v155 offset:1024
	ds_read_b128 v[216:219], v155 offset:2048
	ds_read_b128 v[220:223], v155 offset:3072
	ds_read_b128 v[228:231], v155 offset:4096
	ds_read_b128 v[232:235], v155 offset:5120
	ds_read_b128 v[236:239], v155 offset:6144
	ds_read_b128 v[240:243], v155 offset:7168
	global_load_lds_dwordx4 v[224:225], off
	v_lshl_add_u64 v[224:225], s[6:7], 0, v[148:149]
	s_mov_b32 m0, s2
	s_nop 0
	global_load_lds_dwordx4 v[224:225], off
	s_waitcnt vmcnt(8)
	s_waitcnt lgkmcnt(0)
	s_barrier
	s_setprio 1
	s_waitcnt lgkmcnt(0)
	v_mfma_f32_16x16x32_f16 v[124:127], v[156:159], v[208:211], 0
	v_mfma_f32_16x16x32_f16 v[120:123], v[164:167], v[208:211], 0
	v_mfma_f32_16x16x32_f16 v[108:111], v[156:159], v[216:219], 0
	v_mfma_f32_16x16x32_f16 v[104:107], v[164:167], v[216:219], 0
	v_mfma_f32_16x16x32_f16 v[92:95], v[156:159], v[228:231], 0
	v_mfma_f32_16x16x32_f16 v[88:91], v[164:167], v[228:231], 0
	v_mfma_f32_16x16x32_f16 v[76:79], v[156:159], v[236:239], 0
	v_mfma_f32_16x16x32_f16 v[72:75], v[164:167], v[236:239], 0
	v_mfma_f32_16x16x32_f16 v[124:127], v[160:163], v[212:215], v[124:127]
	v_mfma_f32_16x16x32_f16 v[120:123], v[168:171], v[212:215], v[120:123]
	v_mfma_f32_16x16x32_f16 v[108:111], v[160:163], v[220:223], v[108:111]
	v_mfma_f32_16x16x32_f16 v[104:107], v[168:171], v[220:223], v[104:107]
	v_mfma_f32_16x16x32_f16 v[92:95], v[160:163], v[232:235], v[92:95]
	v_mfma_f32_16x16x32_f16 v[88:91], v[168:171], v[232:235], v[88:91]
	v_mfma_f32_16x16x32_f16 v[76:79], v[160:163], v[240:243], v[76:79]
	v_mfma_f32_16x16x32_f16 v[72:75], v[168:171], v[240:243], v[72:75]
	s_setprio 0
	s_setprio 1
	v_mfma_f32_16x16x32_f16 v[116:119], v[172:175], v[208:211], 0
	v_mfma_f32_16x16x32_f16 v[112:115], v[200:203], v[208:211], 0
	v_mfma_f32_16x16x32_f16 v[100:103], v[172:175], v[216:219], 0
	v_mfma_f32_16x16x32_f16 v[96:99], v[200:203], v[216:219], 0
	v_mfma_f32_16x16x32_f16 v[84:87], v[172:175], v[228:231], 0
	v_mfma_f32_16x16x32_f16 v[80:83], v[200:203], v[228:231], 0
	v_mfma_f32_16x16x32_f16 v[68:71], v[172:175], v[236:239], 0
	v_mfma_f32_16x16x32_f16 v[64:67], v[200:203], v[236:239], 0
	v_mfma_f32_16x16x32_f16 v[116:119], v[176:179], v[212:215], v[116:119]
	v_mfma_f32_16x16x32_f16 v[112:115], v[204:207], v[212:215], v[112:115]
	v_mfma_f32_16x16x32_f16 v[100:103], v[176:179], v[220:223], v[100:103]
	v_mfma_f32_16x16x32_f16 v[96:99], v[204:207], v[220:223], v[96:99]
	v_mfma_f32_16x16x32_f16 v[84:87], v[176:179], v[232:235], v[84:87]
	v_mfma_f32_16x16x32_f16 v[80:83], v[204:207], v[232:235], v[80:83]
	v_mfma_f32_16x16x32_f16 v[68:71], v[176:179], v[240:243], v[68:71]
	v_mfma_f32_16x16x32_f16 v[64:67], v[204:207], v[240:243], v[64:67]
	s_setprio 0
	s_barrier
	s_mov_b32 m0, s53
	v_lshl_add_u64 v[224:225], s[8:9], 0, v[130:131]
	s_add_u32 s78, s8, 0x40000
	ds_read_b128 v[208:211], v155 offset:16384
	ds_read_b128 v[212:215], v155 offset:17408
	ds_read_b128 v[216:219], v155 offset:18432
	ds_read_b128 v[220:223], v155 offset:19456
	ds_read_b128 v[228:231], v155 offset:20480
	ds_read_b128 v[232:235], v155 offset:21504
	ds_read_b128 v[236:239], v155 offset:22528
	ds_read_b128 v[240:243], v155 offset:23552
	global_load_lds_dwordx4 v[224:225], off
	v_lshl_add_u64 v[244:245], s[8:9], 0, v[134:135]
	s_mov_b32 m0, s55
	s_addc_u32 s79, s9, 0
	global_load_lds_dwordx4 v[244:245], off
	v_lshl_add_u64 v[246:247], s[78:79], 0, v[130:131]
	s_mov_b32 m0, s91
	v_lshl_add_u64 v[248:249], s[10:11], 0, v[132:133]
	global_load_lds_dwordx4 v[246:247], off
	v_lshl_add_u64 v[246:247], s[78:79], 0, v[134:135]
	s_mov_b32 m0, s92
	s_nop 0
	global_load_lds_dwordx4 v[246:247], off
	v_lshl_add_u64 v[246:247], s[10:11], 0, v[128:129]
	s_mov_b32 m0, s90
	s_nop 0
	global_load_lds_dwordx4 v[246:247], off
	s_mov_b32 m0, s93
	s_nop 0
	global_load_lds_dwordx4 v[248:249], off
	s_waitcnt vmcnt(8)
	s_waitcnt lgkmcnt(0)
	s_barrier
; #define PG8_STAGE(bufoff, gbase, voff) do { _Pragma("unroll") for (int _i = 0; _i < 2; ++_i) \
;         __builtin_amdgcn_global_load_lds((const unsigned*)((const char*)(gbase) + (voff)[_i]), (PG8_LAS unsigned*)(lds + (bufoff) + ldsw + _i * 8192), 16, 0, 0); } while (0)
; #define PG8_LDA(dst, b, h) do { _Pragma("unroll") for (int m = 0; m < 4; ++m) _Pragma("unroll") for (int k = 0; k < 2; ++k) dst[m][k] = *(const PG8_LAS bf16x8*)(lds + PG8_SA(b, h) + aoff + m * 2048 + k * 1024); } while (0)
; #define PG8_LDB(dst, b, h) do { _Pragma("unroll") for (int n = 0; n < 2; ++n) _Pragma("unroll") for (int k = 0; k < 2; ++k) dst[n][k] = *(const PG8_LAS bf16x8*)(lds + PG8_SB(b, h) + boff + n * 2048 + k * 1024); } while (0)
; #define PG8_MMA(ai, bj, At, Bt) do { __builtin_amdgcn_s_setprio(1); _Pragma("unroll") for (int m = 0; m < 4; ++m) _Pragma("unroll") for (int n = 0; n < 2; ++n) _Pragma("unroll") for (int k = 0; k < 2; ++k) \
;         acc[ai][bj][m][n] = mma16<F16>(Bt[n][k], At[m][k], acc[ai][bj][m][n]); __builtin_amdgcn_s_setprio(0); } while (0)
; #define PG8_WAIT_V(n) asm volatile("s_waitcnt vmcnt(" #n ")" ::: "memory")
; #define PG8_WAIT_L(n) asm volatile("s_waitcnt lgkmcnt(" #n ")" ::: "memory")
; #define PG8_BAR __builtin_amdgcn_s_barrier()
; #define PG8_SCHED __builtin_amdgcn_sched_barrier(0)
; template <class Epi, class Sched, bool ALIGN_EPI = false, bool SP2 = false, bool F16 = false, bool TOKPERM = false>
; __device__ __forceinline__ void gemm_phase(PG8_LAS unsigned char* lds, const Gemm g, const Sched& S, const Epi& E, int wv) {
;     ...
;             PG8_WAIT_V(8); PG8_WAIT_L(0); PG8_BAR; PG8_MMA(1, 0, At, B0); PG8_MMA(1, 1, At, B1); PG8_BAR; PG8_SCHED;
;             PG8_LDB(B0, 1, 0); PG8_LDB(B1, 1, 1); PG8_SCHED; PG8_LDA(At, 1, 0); PG8_STAGE(PG8_SA(0, 1), a2 + hstep, voffA);
;             PG8_WAIT_V(8); PG8_WAIT_L(0); PG8_BAR; PG8_MMA(0, 0, At, B0); PG8_MMA(0, 1, At, B1); PG8_BAR; PG8_SCHED;
	s_setprio 1
	s_waitcnt lgkmcnt(0)
	v_mfma_f32_16x16x32_f16 v[60:63], v[156:159], v[208:211], 0
	v_mfma_f32_16x16x32_f16 v[56:59], v[164:167], v[208:211], 0
	v_mfma_f32_16x16x32_f16 v[44:47], v[156:159], v[216:219], 0
	v_mfma_f32_16x16x32_f16 v[40:43], v[164:167], v[216:219], 0
	v_mfma_f32_16x16x32_f16 v[28:31], v[156:159], v[228:231], 0
	v_mfma_f32_16x16x32_f16 v[24:27], v[164:167], v[228:231], 0
	v_mfma_f32_16x16x32_f16 v[12:15], v[156:159], v[236:239], 0
	v_mfma_f32_16x16x32_f16 v[8:11], v[164:167], v[236:239], 0
	v_mfma_f32_16x16x32_f16 v[60:63], v[160:163], v[212:215], v[60:63]
	v_mfma_f32_16x16x32_f16 v[56:59], v[168:171], v[212:215], v[56:59]
	v_mfma_f32_16x16x32_f16 v[44:47], v[160:163], v[220:223], v[44:47]
	v_mfma_f32_16x16x32_f16 v[40:43], v[168:171], v[220:223], v[40:43]
	v_mfma_f32_16x16x32_f16 v[28:31], v[160:163], v[232:235], v[28:31]
	v_mfma_f32_16x16x32_f16 v[24:27], v[168:171], v[232:235], v[24:27]
	v_mfma_f32_16x16x32_f16 v[12:15], v[160:163], v[240:243], v[12:15]
	v_mfma_f32_16x16x32_f16 v[8:11], v[168:171], v[240:243], v[8:11]
	s_setprio 0
	s_setprio 1
	v_mfma_f32_16x16x32_f16 v[52:55], v[172:175], v[208:211], 0
	v_mfma_f32_16x16x32_f16 v[48:51], v[200:203], v[208:211], 0
	v_mfma_f32_16x16x32_f16 v[36:39], v[172:175], v[216:219], 0
	v_mfma_f32_16x16x32_f16 v[32:35], v[200:203], v[216:219], 0
	v_mfma_f32_16x16x32_f16 v[20:23], v[172:175], v[228:231], 0
	v_mfma_f32_16x16x32_f16 v[16:19], v[200:203], v[228:231], 0
	v_mfma_f32_16x16x32_f16 v[4:7], v[172:175], v[236:239], 0
	v_mfma_f32_16x16x32_f16 v[0:3], v[200:203], v[236:239], 0
	v_mfma_f32_16x16x32_f16 v[52:55], v[176:179], v[212:215], v[52:55]
	v_mfma_f32_16x16x32_f16 v[48:51], v[204:207], v[212:215], v[48:51]
	v_mfma_f32_16x16x32_f16 v[36:39], v[176:179], v[220:223], v[36:39]
	v_mfma_f32_16x16x32_f16 v[32:35], v[204:207], v[220:223], v[32:35]
	v_mfma_f32_16x16x32_f16 v[20:23], v[176:179], v[232:235], v[20:23]
	v_mfma_f32_16x16x32_f16 v[16:19], v[204:207], v[232:235], v[16:19]
	v_mfma_f32_16x16x32_f16 v[4:7], v[176:179], v[240:243], v[4:7]
	v_mfma_f32_16x16x32_f16 v[0:3], v[204:207], v[240:243], v[0:3]
	s_setprio 0
	s_barrier
	ds_read_b128 v[156:159], v189
	ds_read_b128 v[160:163], v190
	ds_read_b128 v[164:167], v191
	ds_read_b128 v[168:171], v192
	ds_read_b128 v[172:175], v193
	ds_read_b128 v[176:179], v194
	ds_read_b128 v[200:203], v195
	ds_read_b128 v[204:207], v196
	s_add_u32 s10, s10, 0x40000
	s_addc_u32 s11, s11, 0
	s_mov_b32 m0, s95
	v_lshl_add_u64 v[250:251], s[10:11], 0, v[128:129]
	ds_read_b128 v[208:211], v155 offset:32768
	ds_read_b128 v[212:215], v155 offset:33792
	ds_read_b128 v[216:219], v155 offset:34816
	ds_read_b128 v[220:223], v155 offset:35840
	ds_read_b128 v[228:231], v155 offset:36864
	ds_read_b128 v[232:235], v155 offset:37888
	ds_read_b128 v[236:239], v155 offset:38912
	ds_read_b128 v[240:243], v155 offset:39936
	global_load_lds_dwordx4 v[250:251], off
	v_lshl_add_u64 v[250:251], s[10:11], 0, v[132:133]
	s_mov_b32 m0, s96
	s_nop 0
	global_load_lds_dwordx4 v[250:251], off
	s_waitcnt vmcnt(8)
	s_waitcnt lgkmcnt(0)
	s_barrier
	s_setprio 1
	s_waitcnt lgkmcnt(0)
	v_mfma_f32_16x16x32_f16 v[124:127], v[156:159], v[208:211], v[124:127]
	v_mfma_f32_16x16x32_f16 v[120:123], v[164:167], v[208:211], v[120:123]
	v_mfma_f32_16x16x32_f16 v[108:111], v[156:159], v[216:219], v[108:111]
	v_mfma_f32_16x16x32_f16 v[104:107], v[164:167], v[216:219], v[104:107]
	v_mfma_f32_16x16x32_f16 v[92:95], v[156:159], v[228:231], v[92:95]
	v_mfma_f32_16x16x32_f16 v[88:91], v[164:167], v[228:231], v[88:91]
	v_mfma_f32_16x16x32_f16 v[76:79], v[156:159], v[236:239], v[76:79]
	v_mfma_f32_16x16x32_f16 v[72:75], v[164:167], v[236:239], v[72:75]
	v_mfma_f32_16x16x32_f16 v[124:127], v[160:163], v[212:215], v[124:127]
	v_mfma_f32_16x16x32_f16 v[120:123], v[168:171], v[212:215], v[120:123]
	v_mfma_f32_16x16x32_f16 v[108:111], v[160:163], v[220:223], v[108:111]
	v_mfma_f32_16x16x32_f16 v[104:107], v[168:171], v[220:223], v[104:107]
	v_mfma_f32_16x16x32_f16 v[92:95], v[160:163], v[232:235], v[92:95]
	v_mfma_f32_16x16x32_f16 v[88:91], v[168:171], v[232:235], v[88:91]
	v_mfma_f32_16x16x32_f16 v[76:79], v[160:163], v[240:243], v[76:79]
	v_mfma_f32_16x16x32_f16 v[72:75], v[168:171], v[240:243], v[72:75]
	s_setprio 0
	s_setprio 1
	v_mfma_f32_16x16x32_f16 v[116:119], v[172:175], v[208:211], v[116:119]
	v_mfma_f32_16x16x32_f16 v[112:115], v[200:203], v[208:211], v[112:115]
	v_mfma_f32_16x16x32_f16 v[100:103], v[172:175], v[216:219], v[100:103]
	v_mfma_f32_16x16x32_f16 v[96:99], v[200:203], v[216:219], v[96:99]
	v_mfma_f32_16x16x32_f16 v[84:87], v[172:175], v[228:231], v[84:87]
	v_mfma_f32_16x16x32_f16 v[80:83], v[200:203], v[228:231], v[80:83]
	v_mfma_f32_16x16x32_f16 v[68:71], v[172:175], v[236:239], v[68:71]
	v_mfma_f32_16x16x32_f16 v[64:67], v[200:203], v[236:239], v[64:67]
	v_mfma_f32_16x16x32_f16 v[116:119], v[176:179], v[212:215], v[116:119]
	v_mfma_f32_16x16x32_f16 v[112:115], v[204:207], v[212:215], v[112:115]
	v_mfma_f32_16x16x32_f16 v[100:103], v[176:179], v[220:223], v[100:103]
	v_mfma_f32_16x16x32_f16 v[96:99], v[204:207], v[220:223], v[96:99]
	v_mfma_f32_16x16x32_f16 v[84:87], v[176:179], v[232:235], v[84:87]
	v_mfma_f32_16x16x32_f16 v[80:83], v[204:207], v[232:235], v[80:83]
	v_mfma_f32_16x16x32_f16 v[68:71], v[176:179], v[240:243], v[68:71]
	v_mfma_f32_16x16x32_f16 v[64:67], v[204:207], v[240:243], v[64:67]
	s_setprio 0
	s_barrier
; #define PG8_STAGE(bufoff, gbase, voff) do { _Pragma("unroll") for (int _i = 0; _i < 2; ++_i) \
;         __builtin_amdgcn_global_load_lds((const unsigned*)((const char*)(gbase) + (voff)[_i]), (PG8_LAS unsigned*)(lds + (bufoff) + ldsw + _i * 8192), 16, 0, 0); } while (0)
; #define PG8_LDA(dst, b, h) do { _Pragma("unroll") for (int m = 0; m < 4; ++m) _Pragma("unroll") for (int k = 0; k < 2; ++k) dst[m][k] = *(const PG8_LAS bf16x8*)(lds + PG8_SA(b, h) + aoff + m * 2048 + k * 1024); } while (0)
; #define PG8_MMA(ai, bj, At, Bt) do { __builtin_amdgcn_s_setprio(1); _Pragma("unroll") for (int m = 0; m < 4; ++m) _Pragma("unroll") for (int n = 0; n < 2; ++n) _Pragma("unroll") for (int k = 0; k < 2; ++k) \
;         acc[ai][bj][m][n] = mma16<F16>(Bt[n][k], At[m][k], acc[ai][bj][m][n]); __builtin_amdgcn_s_setprio(0); } while (0)
; #define PG8_WAIT_V(n) asm volatile("s_waitcnt vmcnt(" #n ")" ::: "memory")
; #define PG8_WAIT_L(n) asm volatile("s_waitcnt lgkmcnt(" #n ")" ::: "memory")
; #define PG8_BAR __builtin_amdgcn_s_barrier()
; #define PG8_SCHED __builtin_amdgcn_sched_barrier(0)
; template <class Epi, class Sched, bool ALIGN_EPI = false, bool SP2 = false, bool F16 = false, bool TOKPERM = false>
; __device__ __forceinline__ void gemm_phase(PG8_LAS unsigned char* lds, const Gemm g, const Sched& S, const Epi& E, int wv) {
;     ...
;             PG8_LDA(At, 1, 1); PG8_STAGE(PG8_SB(1, 0), b3, voffB); PG8_STAGE(PG8_SB(1, 1), b3 + hstep, voffB); PG8_STAGE(PG8_SA(1, 0), a3, voffA);
;             PG8_WAIT_V(8); PG8_WAIT_L(0); PG8_BAR; PG8_MMA(1, 0, At, B0); PG8_MMA(1, 1, At, B1); PG8_BAR; PG8_SCHED;
	s_mov_b32 m0, s20
	v_lshl_add_u64 v[224:225], v[224:225], 0, s[60:61]
	s_add_u32 s8, s8, 0x40080
	ds_read_b128 v[208:211], v155 offset:49152
	ds_read_b128 v[212:215], v155 offset:50176
	ds_read_b128 v[216:219], v155 offset:51200
	ds_read_b128 v[220:223], v155 offset:52224
	ds_read_b128 v[228:231], v155 offset:53248
	ds_read_b128 v[232:235], v155 offset:54272
	ds_read_b128 v[236:239], v155 offset:55296
	ds_read_b128 v[240:243], v155 offset:56320
	global_load_lds_dwordx4 v[224:225], off
	v_lshl_add_u64 v[224:225], v[244:245], 0, s[60:61]
	s_mov_b32 m0, s21
	s_addc_u32 s9, s9, 0
	global_load_lds_dwordx4 v[224:225], off
	v_lshl_add_u64 v[224:225], s[8:9], 0, v[130:131]
	s_mov_b32 m0, s44
	s_nop 0
	global_load_lds_dwordx4 v[224:225], off
	v_lshl_add_u64 v[224:225], s[8:9], 0, v[134:135]
	s_mov_b32 m0, s45
	s_nop 0
	global_load_lds_dwordx4 v[224:225], off
	v_lshl_add_u64 v[224:225], v[246:247], 0, s[60:61]
	s_mov_b32 m0, s22
	s_nop 0
	global_load_lds_dwordx4 v[224:225], off
	v_lshl_add_u64 v[224:225], v[248:249], 0, s[60:61]
	s_mov_b32 m0, s23
	s_nop 0
	global_load_lds_dwordx4 v[224:225], off
	s_waitcnt vmcnt(8)
	s_waitcnt lgkmcnt(0)
	s_barrier
	s_setprio 1
	s_waitcnt lgkmcnt(0)
	v_mfma_f32_16x16x32_f16 v[60:63], v[156:159], v[208:211], v[60:63]
	v_mfma_f32_16x16x32_f16 v[56:59], v[164:167], v[208:211], v[56:59]
	v_mfma_f32_16x16x32_f16 v[44:47], v[156:159], v[216:219], v[44:47]
	v_mfma_f32_16x16x32_f16 v[40:43], v[164:167], v[216:219], v[40:43]
	v_mfma_f32_16x16x32_f16 v[28:31], v[156:159], v[228:231], v[28:31]
	v_mfma_f32_16x16x32_f16 v[24:27], v[164:167], v[228:231], v[24:27]
	v_mfma_f32_16x16x32_f16 v[12:15], v[156:159], v[236:239], v[12:15]
	v_mfma_f32_16x16x32_f16 v[8:11], v[164:167], v[236:239], v[8:11]
	v_mfma_f32_16x16x32_f16 v[60:63], v[160:163], v[212:215], v[60:63]
	v_mfma_f32_16x16x32_f16 v[56:59], v[168:171], v[212:215], v[56:59]
	v_mfma_f32_16x16x32_f16 v[44:47], v[160:163], v[220:223], v[44:47]
	v_mfma_f32_16x16x32_f16 v[40:43], v[168:171], v[220:223], v[40:43]
	v_mfma_f32_16x16x32_f16 v[28:31], v[160:163], v[232:235], v[28:31]
	v_mfma_f32_16x16x32_f16 v[24:27], v[168:171], v[232:235], v[24:27]
	v_mfma_f32_16x16x32_f16 v[12:15], v[160:163], v[240:243], v[12:15]
	v_mfma_f32_16x16x32_f16 v[8:11], v[168:171], v[240:243], v[8:11]
	s_setprio 0
	s_setprio 1
	v_mfma_f32_16x16x32_f16 v[52:55], v[172:175], v[208:211], v[52:55]
	v_mfma_f32_16x16x32_f16 v[48:51], v[200:203], v[208:211], v[48:51]
	v_mfma_f32_16x16x32_f16 v[36:39], v[172:175], v[216:219], v[36:39]
	v_mfma_f32_16x16x32_f16 v[32:35], v[200:203], v[216:219], v[32:35]
	v_mfma_f32_16x16x32_f16 v[20:23], v[172:175], v[228:231], v[20:23]
	v_mfma_f32_16x16x32_f16 v[16:19], v[200:203], v[228:231], v[16:19]
	v_mfma_f32_16x16x32_f16 v[4:7], v[172:175], v[236:239], v[4:7]
	v_mfma_f32_16x16x32_f16 v[0:3], v[200:203], v[236:239], v[0:3]
	v_mfma_f32_16x16x32_f16 v[52:55], v[176:179], v[212:215], v[52:55]
	v_mfma_f32_16x16x32_f16 v[48:51], v[204:207], v[212:215], v[48:51]
	v_mfma_f32_16x16x32_f16 v[36:39], v[176:179], v[220:223], v[36:39]
	v_mfma_f32_16x16x32_f16 v[32:35], v[204:207], v[220:223], v[32:35]
	v_mfma_f32_16x16x32_f16 v[20:23], v[176:179], v[232:235], v[20:23]
	v_mfma_f32_16x16x32_f16 v[16:19], v[204:207], v[232:235], v[16:19]
	v_mfma_f32_16x16x32_f16 v[4:7], v[176:179], v[240:243], v[4:7]
	v_mfma_f32_16x16x32_f16 v[0:3], v[204:207], v[240:243], v[0:3]
	s_setprio 0
	s_barrier
	s_add_i32 s76, s76, 2
	s_add_u32 s6, s6, 0x100
	s_addc_u32 s7, s7, 0
	s_add_u32 s69, s69, 0x100
	s_addc_u32 s71, s71, 0
	s_cmp_gt_u32 s76, 13

; #define PG8_STAGE(bufoff, gbase, voff) do { _Pragma("unroll") for (int _i = 0; _i < 2; ++_i) \
;         __builtin_amdgcn_global_load_lds((const unsigned*)((const char*)(gbase) + (voff)[_i]), (PG8_LAS unsigned*)(lds + (bufoff) + ldsw + _i * 8192), 16, 0, 0); } while (0)
; #define PG8_LDA(dst, b, h) do { _Pragma("unroll") for (int m = 0; m < 4; ++m) _Pragma("unroll") for (int k = 0; k < 2; ++k) dst[m][k] = *(const PG8_LAS bf16x8*)(lds + PG8_SA(b, h) + aoff + m * 2048 + k * 1024); } while (0)
; #define PG8_LDB(dst, b, h) do { _Pragma("unroll") for (int n = 0; n < 2; ++n) _Pragma("unroll") for (int k = 0; k < 2; ++k) dst[n][k] = *(const PG8_LAS bf16x8*)(lds + PG8_SB(b, h) + boff + n * 2048 + k * 1024); } while (0)
; #define PG8_WAIT_V(n) asm volatile("s_waitcnt vmcnt(" #n ")" ::: "memory")
; #define PG8_WAIT_L(n) asm volatile("s_waitcnt lgkmcnt(" #n ")" ::: "memory")
; #define PG8_BAR __builtin_amdgcn_s_barrier()
; #define PG8_SCHED __builtin_amdgcn_sched_barrier(0)
; template <class Epi, class Sched, bool ALIGN_EPI = false, bool SP2 = false, bool F16 = false, bool TOKPERM = false>
; __device__ __forceinline__ void gemm_phase(PG8_LAS unsigned char* lds, const Gemm g, const Sched& S, const Epi& E, int wv) {
;     ...
;         const bool has_next = S.next(ui + 1, nxt);
;         const char* nA = has_next ? (const char*)g.A + (size_t)nxt.pm * tstep : cA; const char* nB = has_next ? (const char*)g.Bt + (size_t)nxt.pn * tstep : cB;
;         for (int t = 0; t < nt; t += 2) {
;             const bool last = (t == nt - 2);
;             const char* a1 = cA + (size_t)(t + 1) * kstep;
;             const char* a2 = last ? nA : cA + (size_t)(t + 2) * kstep; const char* b2 = last ? nB : cB + (size_t)(t + 2) * kstep;
;             const char* a3 = a2 + kstep; const char* b3 = b2 + kstep;
;             if (last && has_next) S.a_ready(nxt);
;             if constexpr (SP2) {
;             PG8_LDB(B0, 0, 0); PG8_LDB(B1, 0, 1); PG8_SCHED; PG8_LDA(At, 0, 0); PG8_STAGE(PG8_SA(1, 1), a1 + hstep, voffA);
;             PG8_WAIT_V(8); PG8_WAIT_L(0); PG8_BAR; PG8_MMA(0, 0, At, B0); PG8_MMA(0, 1, At, B1); PG8_BAR; PG8_SCHED;
;             PG8_LDA(At, 0, 1); PG8_STAGE(PG8_SB(0, 0), b2, voffB); PG8_STAGE(PG8_SB(0, 1), b2 + hstep, voffB); PG8_STAGE(PG8_SA(0, 0), a2, voffA);
;             PG8_WAIT_V(8); PG8_WAIT_L(0); PG8_BAR; PG8_MMA(1, 0, At, B0); PG8_MMA(1, 1, At, B1); PG8_BAR; PG8_SCHED;
.LBB0_767:
	s_ashr_i32 s53, s52, 31
	s_lshl_b64 s[54:55], s[52:53], 19
	s_add_u32 s54, s40, s54
	s_addc_u32 s55, s41, s55
	s_and_b64 s[56:57], s[6:7], exec
	s_cselect_b32 s53, s55, s11
	s_cselect_b32 s70, s54, s10
	s_ashr_i32 s51, s50, 31
	s_lshl_b64 s[56:57], s[50:51], 19
	s_add_u32 s56, s0, s56
	s_addc_u32 s57, s1, s57
	s_and_b64 s[58:59], s[6:7], exec
	s_cselect_b32 s51, s57, s13
	s_cselect_b32 s71, s56, s12
	s_add_u32 s10, s10, 0x40080
	s_addc_u32 s11, s11, 0
	s_add_u32 s72, s12, 0x100
	s_addc_u32 s73, s13, 0
	s_mov_b32 s74, -2
	ds_read_b128 v[172:175], v155
	ds_read_b128 v[176:179], v156
	ds_read_b128 v[180:183], v157
	ds_read_b128 v[184:187], v158
	ds_read_b128 v[188:191], v159
	ds_read_b128 v[192:195], v160
	ds_read_b128 v[196:199], v161
	ds_read_b128 v[200:203], v162
	s_add_u32 s12, s10, 0xfffc0080
	s_addc_u32 s13, s11, -1
	s_cmp_eq_u32 s74, 12
	s_cselect_b32 s59, s53, s13
	s_cselect_b32 s58, s70, s12
	s_cselect_b32 s13, s51, s73
	s_cselect_b32 s12, s71, s72
	s_mov_b32 m0, s66
	v_lshl_add_u64 v[148:149], s[10:11], 0, v[140:141]
	ds_read_b128 v[204:207], v153
	ds_read_b128 v[208:211], v153 offset:1024
	ds_read_b128 v[212:215], v153 offset:2048
	ds_read_b128 v[216:219], v153 offset:3072
	ds_read_b128 v[220:223], v153 offset:4096
	ds_read_b128 v[228:231], v153 offset:5120
	ds_read_b128 v[232:235], v153 offset:6144
	ds_read_b128 v[236:239], v153 offset:7168
	global_load_lds_dwordx4 v[148:149], off
	v_lshl_add_u64 v[148:149], s[10:11], 0, v[142:143]
	s_mov_b32 m0, s67
	s_nop 0
	global_load_lds_dwordx4 v[148:149], off
	s_waitcnt vmcnt(8)
	s_waitcnt lgkmcnt(0)
	s_barrier
	s_setprio 1
	s_waitcnt lgkmcnt(0)
	v_mfma_f32_16x16x32_f16 v[124:127], v[172:175], v[204:207], 0
	v_mfma_f32_16x16x32_f16 v[116:119], v[180:183], v[204:207], 0
	v_mfma_f32_16x16x32_f16 v[108:111], v[172:175], v[212:215], 0
	v_mfma_f32_16x16x32_f16 v[104:107], v[180:183], v[212:215], 0
	v_mfma_f32_16x16x32_f16 v[92:95], v[172:175], v[220:223], 0
	v_mfma_f32_16x16x32_f16 v[88:91], v[180:183], v[220:223], 0
	v_mfma_f32_16x16x32_f16 v[76:79], v[172:175], v[232:235], 0
	v_mfma_f32_16x16x32_f16 v[72:75], v[180:183], v[232:235], 0
	v_mfma_f32_16x16x32_f16 v[124:127], v[176:179], v[208:211], v[124:127]
	v_mfma_f32_16x16x32_f16 v[116:119], v[184:187], v[208:211], v[116:119]
	v_mfma_f32_16x16x32_f16 v[108:111], v[176:179], v[216:219], v[108:111]
	v_mfma_f32_16x16x32_f16 v[104:107], v[184:187], v[216:219], v[104:107]
	v_mfma_f32_16x16x32_f16 v[92:95], v[176:179], v[228:231], v[92:95]
	v_mfma_f32_16x16x32_f16 v[88:91], v[184:187], v[228:231], v[88:91]
	v_mfma_f32_16x16x32_f16 v[76:79], v[176:179], v[236:239], v[76:79]
	v_mfma_f32_16x16x32_f16 v[72:75], v[184:187], v[236:239], v[72:75]
	s_setprio 0
	s_setprio 1
	v_mfma_f32_16x16x32_f16 v[120:123], v[188:191], v[204:207], 0
	v_mfma_f32_16x16x32_f16 v[112:115], v[196:199], v[204:207], 0
	v_mfma_f32_16x16x32_f16 v[100:103], v[188:191], v[212:215], 0
	v_mfma_f32_16x16x32_f16 v[96:99], v[196:199], v[212:215], 0
	v_mfma_f32_16x16x32_f16 v[84:87], v[188:191], v[220:223], 0
	v_mfma_f32_16x16x32_f16 v[80:83], v[196:199], v[220:223], 0
	v_mfma_f32_16x16x32_f16 v[68:71], v[188:191], v[232:235], 0
	v_mfma_f32_16x16x32_f16 v[64:67], v[196:199], v[232:235], 0
	v_mfma_f32_16x16x32_f16 v[120:123], v[192:195], v[208:211], v[120:123]
	v_mfma_f32_16x16x32_f16 v[112:115], v[200:203], v[208:211], v[112:115]
	v_mfma_f32_16x16x32_f16 v[100:103], v[192:195], v[216:219], v[100:103]
	v_mfma_f32_16x16x32_f16 v[96:99], v[200:203], v[216:219], v[96:99]
	v_mfma_f32_16x16x32_f16 v[84:87], v[192:195], v[228:231], v[84:87]
	v_mfma_f32_16x16x32_f16 v[80:83], v[200:203], v[228:231], v[80:83]
	v_mfma_f32_16x16x32_f16 v[68:71], v[192:195], v[236:239], v[68:71]
	v_mfma_f32_16x16x32_f16 v[64:67], v[200:203], v[236:239], v[64:67]
	s_setprio 0
	s_barrier
	s_mov_b32 m0, s5
	v_lshl_add_u64 v[148:149], s[12:13], 0, v[132:133]
	s_add_u32 s76, s12, 0x40000
	ds_read_b128 v[204:207], v153 offset:16384
	ds_read_b128 v[208:211], v153 offset:17408
	ds_read_b128 v[212:215], v153 offset:18432
	ds_read_b128 v[216:219], v153 offset:19456
	ds_read_b128 v[220:223], v153 offset:20480
	ds_read_b128 v[228:231], v153 offset:21504
	ds_read_b128 v[232:235], v153 offset:22528
	ds_read_b128 v[236:239], v153 offset:23552
	global_load_lds_dwordx4 v[148:149], off
	v_lshl_add_u64 v[224:225], s[12:13], 0, v[128:129]
	s_mov_b32 m0, s21
	s_addc_u32 s77, s13, 0
	global_load_lds_dwordx4 v[224:225], off
	v_lshl_add_u64 v[240:241], s[76:77], 0, v[132:133]
	s_mov_b32 m0, s22
	v_lshl_add_u64 v[242:243], s[58:59], 0, v[130:131]
	global_load_lds_dwordx4 v[240:241], off
	v_lshl_add_u64 v[240:241], s[76:77], 0, v[128:129]
	s_mov_b32 m0, s23
	s_nop 0
	global_load_lds_dwordx4 v[240:241], off
	v_lshl_add_u64 v[240:241], s[58:59], 0, v[134:135]
	s_mov_b32 m0, s2
	s_nop 0
	global_load_lds_dwordx4 v[240:241], off
	s_mov_b32 m0, s33
	s_nop 0
	global_load_lds_dwordx4 v[242:243], off
	s_waitcnt vmcnt(8)
	s_waitcnt lgkmcnt(0)
	s_barrier
; #define PG8_STAGE(bufoff, gbase, voff) do { _Pragma("unroll") for (int _i = 0; _i < 2; ++_i) \
;         __builtin_amdgcn_global_load_lds((const unsigned*)((const char*)(gbase) + (voff)[_i]), (PG8_LAS unsigned*)(lds + (bufoff) + ldsw + _i * 8192), 16, 0, 0); } while (0)
; #define PG8_LDA(dst, b, h) do { _Pragma("unroll") for (int m = 0; m < 4; ++m) _Pragma("unroll") for (int k = 0; k < 2; ++k) dst[m][k] = *(const PG8_LAS bf16x8*)(lds + PG8_SA(b, h) + aoff + m * 2048 + k * 1024); } while (0)
; #define PG8_LDB(dst, b, h) do { _Pragma("unroll") for (int n = 0; n < 2; ++n) _Pragma("unroll") for (int k = 0; k < 2; ++k) dst[n][k] = *(const PG8_LAS bf16x8*)(lds + PG8_SB(b, h) + boff + n * 2048 + k * 1024); } while (0)
; #define PG8_MMA(ai, bj, At, Bt) do { __builtin_amdgcn_s_setprio(1); _Pragma("unroll") for (int m = 0; m < 4; ++m) _Pragma("unroll") for (int n = 0; n < 2; ++n) _Pragma("unroll") for (int k = 0; k < 2; ++k) \
;         acc[ai][bj][m][n] = mma16<F16>(Bt[n][k], At[m][k], acc[ai][bj][m][n]); __builtin_amdgcn_s_setprio(0); } while (0)
; #define PG8_WAIT_V(n) asm volatile("s_waitcnt vmcnt(" #n ")" ::: "memory")
; #define PG8_WAIT_L(n) asm volatile("s_waitcnt lgkmcnt(" #n ")" ::: "memory")
; #define PG8_BAR __builtin_amdgcn_s_barrier()
; #define PG8_SCHED __builtin_amdgcn_sched_barrier(0)
; template <class Epi, class Sched, bool ALIGN_EPI = false, bool SP2 = false, bool F16 = false, bool TOKPERM = false>
; __device__ __forceinline__ void gemm_phase(PG8_LAS unsigned char* lds, const Gemm g, const Sched& S, const Epi& E, int wv) {
;     ...
;             PG8_WAIT_V(8); PG8_WAIT_L(0); PG8_BAR; PG8_MMA(1, 0, At, B0); PG8_MMA(1, 1, At, B1); PG8_BAR; PG8_SCHED;
;             PG8_LDB(B0, 1, 0); PG8_LDB(B1, 1, 1); PG8_SCHED; PG8_LDA(At, 1, 0); PG8_STAGE(PG8_SA(0, 1), a2 + hstep, voffA);
;             PG8_WAIT_V(8); PG8_WAIT_L(0); PG8_BAR; PG8_MMA(0, 0, At, B0); PG8_MMA(0, 1, At, B1); PG8_BAR; PG8_SCHED;
	s_setprio 1
	s_waitcnt lgkmcnt(0)
	v_mfma_f32_16x16x32_f16 v[60:63], v[172:175], v[204:207], 0
	v_mfma_f32_16x16x32_f16 v[56:59], v[180:183], v[204:207], 0
	v_mfma_f32_16x16x32_f16 v[44:47], v[172:175], v[212:215], 0
	v_mfma_f32_16x16x32_f16 v[40:43], v[180:183], v[212:215], 0
	v_mfma_f32_16x16x32_f16 v[28:31], v[172:175], v[220:223], 0
	v_mfma_f32_16x16x32_f16 v[24:27], v[180:183], v[220:223], 0
	v_mfma_f32_16x16x32_f16 v[12:15], v[172:175], v[232:235], 0
	v_mfma_f32_16x16x32_f16 v[8:11], v[180:183], v[232:235], 0
	v_mfma_f32_16x16x32_f16 v[60:63], v[176:179], v[208:211], v[60:63]
	v_mfma_f32_16x16x32_f16 v[56:59], v[184:187], v[208:211], v[56:59]
	v_mfma_f32_16x16x32_f16 v[44:47], v[176:179], v[216:219], v[44:47]
	v_mfma_f32_16x16x32_f16 v[40:43], v[184:187], v[216:219], v[40:43]
	v_mfma_f32_16x16x32_f16 v[28:31], v[176:179], v[228:231], v[28:31]
	v_mfma_f32_16x16x32_f16 v[24:27], v[184:187], v[228:231], v[24:27]
	v_mfma_f32_16x16x32_f16 v[12:15], v[176:179], v[236:239], v[12:15]
	v_mfma_f32_16x16x32_f16 v[8:11], v[184:187], v[236:239], v[8:11]
	s_setprio 0
	s_setprio 1
	v_mfma_f32_16x16x32_f16 v[52:55], v[188:191], v[204:207], 0
	v_mfma_f32_16x16x32_f16 v[48:51], v[196:199], v[204:207], 0
	v_mfma_f32_16x16x32_f16 v[36:39], v[188:191], v[212:215], 0
	v_mfma_f32_16x16x32_f16 v[32:35], v[196:199], v[212:215], 0
	v_mfma_f32_16x16x32_f16 v[20:23], v[188:191], v[220:223], 0
	v_mfma_f32_16x16x32_f16 v[16:19], v[196:199], v[220:223], 0
	v_mfma_f32_16x16x32_f16 v[4:7], v[188:191], v[232:235], 0
	v_mfma_f32_16x16x32_f16 v[0:3], v[196:199], v[232:235], 0
	v_mfma_f32_16x16x32_f16 v[52:55], v[192:195], v[208:211], v[52:55]
	v_mfma_f32_16x16x32_f16 v[48:51], v[200:203], v[208:211], v[48:51]
	v_mfma_f32_16x16x32_f16 v[36:39], v[192:195], v[216:219], v[36:39]
	v_mfma_f32_16x16x32_f16 v[32:35], v[200:203], v[216:219], v[32:35]
	v_mfma_f32_16x16x32_f16 v[20:23], v[192:195], v[228:231], v[20:23]
	v_mfma_f32_16x16x32_f16 v[16:19], v[200:203], v[228:231], v[16:19]
	v_mfma_f32_16x16x32_f16 v[4:7], v[192:195], v[236:239], v[4:7]
	v_mfma_f32_16x16x32_f16 v[0:3], v[200:203], v[236:239], v[0:3]
	s_setprio 0
	s_barrier
	ds_read_b128 v[172:175], v163
	ds_read_b128 v[176:179], v164
	ds_read_b128 v[180:183], v165
	ds_read_b128 v[184:187], v166
	ds_read_b128 v[188:191], v167
	ds_read_b128 v[192:195], v168
	ds_read_b128 v[196:199], v169
	ds_read_b128 v[200:203], v170
	s_add_u32 s58, s58, 0x40000
	s_addc_u32 s59, s59, 0
	s_mov_b32 m0, s36
	v_lshl_add_u64 v[244:245], s[58:59], 0, v[134:135]
	ds_read_b128 v[204:207], v153 offset:32768
	ds_read_b128 v[208:211], v153 offset:33792
	ds_read_b128 v[212:215], v153 offset:34816
	ds_read_b128 v[216:219], v153 offset:35840
	ds_read_b128 v[220:223], v153 offset:36864
	ds_read_b128 v[228:231], v153 offset:37888
	ds_read_b128 v[232:235], v153 offset:38912
	ds_read_b128 v[236:239], v153 offset:39936
	global_load_lds_dwordx4 v[244:245], off
	v_lshl_add_u64 v[244:245], s[58:59], 0, v[130:131]
	s_mov_b32 m0, s37
	s_nop 0
	global_load_lds_dwordx4 v[244:245], off
	s_waitcnt vmcnt(8)
	s_waitcnt lgkmcnt(0)
	s_barrier
	s_setprio 1
	s_waitcnt lgkmcnt(0)
	v_mfma_f32_16x16x32_f16 v[124:127], v[172:175], v[204:207], v[124:127]
	v_mfma_f32_16x16x32_f16 v[116:119], v[180:183], v[204:207], v[116:119]
	v_mfma_f32_16x16x32_f16 v[108:111], v[172:175], v[212:215], v[108:111]
	v_mfma_f32_16x16x32_f16 v[104:107], v[180:183], v[212:215], v[104:107]
	v_mfma_f32_16x16x32_f16 v[92:95], v[172:175], v[220:223], v[92:95]
	v_mfma_f32_16x16x32_f16 v[88:91], v[180:183], v[220:223], v[88:91]
	v_mfma_f32_16x16x32_f16 v[76:79], v[172:175], v[232:235], v[76:79]
	v_mfma_f32_16x16x32_f16 v[72:75], v[180:183], v[232:235], v[72:75]
	v_mfma_f32_16x16x32_f16 v[124:127], v[176:179], v[208:211], v[124:127]
	v_mfma_f32_16x16x32_f16 v[116:119], v[184:187], v[208:211], v[116:119]
	v_mfma_f32_16x16x32_f16 v[108:111], v[176:179], v[216:219], v[108:111]
	v_mfma_f32_16x16x32_f16 v[104:107], v[184:187], v[216:219], v[104:107]
	v_mfma_f32_16x16x32_f16 v[92:95], v[176:179], v[228:231], v[92:95]
	v_mfma_f32_16x16x32_f16 v[88:91], v[184:187], v[228:231], v[88:91]
	v_mfma_f32_16x16x32_f16 v[76:79], v[176:179], v[236:239], v[76:79]
	v_mfma_f32_16x16x32_f16 v[72:75], v[184:187], v[236:239], v[72:75]
	s_setprio 0
	s_setprio 1
	v_mfma_f32_16x16x32_f16 v[120:123], v[188:191], v[204:207], v[120:123]
	v_mfma_f32_16x16x32_f16 v[112:115], v[196:199], v[204:207], v[112:115]
	v_mfma_f32_16x16x32_f16 v[100:103], v[188:191], v[212:215], v[100:103]
	v_mfma_f32_16x16x32_f16 v[96:99], v[196:199], v[212:215], v[96:99]
	v_mfma_f32_16x16x32_f16 v[84:87], v[188:191], v[220:223], v[84:87]
	v_mfma_f32_16x16x32_f16 v[80:83], v[196:199], v[220:223], v[80:83]
	v_mfma_f32_16x16x32_f16 v[68:71], v[188:191], v[232:235], v[68:71]
	v_mfma_f32_16x16x32_f16 v[64:67], v[196:199], v[232:235], v[64:67]
	v_mfma_f32_16x16x32_f16 v[120:123], v[192:195], v[208:211], v[120:123]
	v_mfma_f32_16x16x32_f16 v[112:115], v[200:203], v[208:211], v[112:115]
	v_mfma_f32_16x16x32_f16 v[100:103], v[192:195], v[216:219], v[100:103]
	v_mfma_f32_16x16x32_f16 v[96:99], v[200:203], v[216:219], v[96:99]
	v_mfma_f32_16x16x32_f16 v[84:87], v[192:195], v[228:231], v[84:87]
	v_mfma_f32_16x16x32_f16 v[80:83], v[200:203], v[228:231], v[80:83]
	v_mfma_f32_16x16x32_f16 v[68:71], v[192:195], v[236:239], v[68:71]
	v_mfma_f32_16x16x32_f16 v[64:67], v[200:203], v[236:239], v[64:67]
	s_setprio 0
	s_barrier
; #define PG8_STAGE(bufoff, gbase, voff) do { _Pragma("unroll") for (int _i = 0; _i < 2; ++_i) \
;         __builtin_amdgcn_global_load_lds((const unsigned*)((const char*)(gbase) + (voff)[_i]), (PG8_LAS unsigned*)(lds + (bufoff) + ldsw + _i * 8192), 16, 0, 0); } while (0)
; #define PG8_LDA(dst, b, h) do { _Pragma("unroll") for (int m = 0; m < 4; ++m) _Pragma("unroll") for (int k = 0; k < 2; ++k) dst[m][k] = *(const PG8_LAS bf16x8*)(lds + PG8_SA(b, h) + aoff + m * 2048 + k * 1024); } while (0)
; #define PG8_MMA(ai, bj, At, Bt) do { __builtin_amdgcn_s_setprio(1); _Pragma("unroll") for (int m = 0; m < 4; ++m) _Pragma("unroll") for (int n = 0; n < 2; ++n) _Pragma("unroll") for (int k = 0; k < 2; ++k) \
;         acc[ai][bj][m][n] = mma16<F16>(Bt[n][k], At[m][k], acc[ai][bj][m][n]); __builtin_amdgcn_s_setprio(0); } while (0)
; #define PG8_WAIT_V(n) asm volatile("s_waitcnt vmcnt(" #n ")" ::: "memory")
; #define PG8_WAIT_L(n) asm volatile("s_waitcnt lgkmcnt(" #n ")" ::: "memory")
; #define PG8_BAR __builtin_amdgcn_s_barrier()
; #define PG8_SCHED __builtin_amdgcn_sched_barrier(0)
; template <class Epi, class Sched, bool ALIGN_EPI = false, bool SP2 = false, bool F16 = false, bool TOKPERM = false>
; __device__ __forceinline__ void gemm_phase(PG8_LAS unsigned char* lds, const Gemm g, const Sched& S, const Epi& E, int wv) {
;     ...
;             PG8_LDA(At, 1, 1); PG8_STAGE(PG8_SB(1, 0), b3, voffB); PG8_STAGE(PG8_SB(1, 1), b3 + hstep, voffB); PG8_STAGE(PG8_SA(1, 0), a3, voffA);
;             PG8_WAIT_V(8); PG8_WAIT_L(0); PG8_BAR; PG8_MMA(1, 0, At, B0); PG8_MMA(1, 1, At, B1); PG8_BAR; PG8_SCHED;
	s_mov_b32 m0, s45
	v_lshl_add_u64 v[148:149], v[148:149], 0, s[16:17]
	s_add_u32 s12, s12, 0x40080
	ds_read_b128 v[204:207], v153 offset:49152
	ds_read_b128 v[208:211], v153 offset:50176
	ds_read_b128 v[212:215], v153 offset:51200
	ds_read_b128 v[216:219], v153 offset:52224
	ds_read_b128 v[220:223], v153 offset:53248
	ds_read_b128 v[228:231], v153 offset:54272
	ds_read_b128 v[232:235], v153 offset:55296
	ds_read_b128 v[236:239], v153 offset:56320
	global_load_lds_dwordx4 v[148:149], off
	v_lshl_add_u64 v[148:149], v[224:225], 0, s[16:17]
	s_mov_b32 m0, s49
	s_addc_u32 s13, s13, 0
	global_load_lds_dwordx4 v[148:149], off
	v_lshl_add_u64 v[148:149], s[12:13], 0, v[132:133]
	s_mov_b32 m0, s62
	s_nop 0
	global_load_lds_dwordx4 v[148:149], off
	v_lshl_add_u64 v[148:149], s[12:13], 0, v[128:129]
	s_mov_b32 m0, s63
	s_nop 0
	global_load_lds_dwordx4 v[148:149], off
	v_lshl_add_u64 v[148:149], v[240:241], 0, s[16:17]
	s_mov_b32 m0, s60
	s_nop 0
	global_load_lds_dwordx4 v[148:149], off
	v_lshl_add_u64 v[148:149], v[242:243], 0, s[16:17]
	s_mov_b32 m0, s61
	s_nop 0
	global_load_lds_dwordx4 v[148:149], off
	s_waitcnt vmcnt(8)
	s_waitcnt lgkmcnt(0)
	s_barrier
	s_setprio 1
	s_waitcnt lgkmcnt(0)
	v_mfma_f32_16x16x32_f16 v[60:63], v[172:175], v[204:207], v[60:63]
	v_mfma_f32_16x16x32_f16 v[56:59], v[180:183], v[204:207], v[56:59]
	v_mfma_f32_16x16x32_f16 v[44:47], v[172:175], v[212:215], v[44:47]
	v_mfma_f32_16x16x32_f16 v[40:43], v[180:183], v[212:215], v[40:43]
	v_mfma_f32_16x16x32_f16 v[28:31], v[172:175], v[220:223], v[28:31]
	v_mfma_f32_16x16x32_f16 v[24:27], v[180:183], v[220:223], v[24:27]
	v_mfma_f32_16x16x32_f16 v[12:15], v[172:175], v[232:235], v[12:15]
	v_mfma_f32_16x16x32_f16 v[8:11], v[180:183], v[232:235], v[8:11]
	v_mfma_f32_16x16x32_f16 v[60:63], v[176:179], v[208:211], v[60:63]
	v_mfma_f32_16x16x32_f16 v[56:59], v[184:187], v[208:211], v[56:59]
	v_mfma_f32_16x16x32_f16 v[44:47], v[176:179], v[216:219], v[44:47]
	v_mfma_f32_16x16x32_f16 v[40:43], v[184:187], v[216:219], v[40:43]
	v_mfma_f32_16x16x32_f16 v[28:31], v[176:179], v[228:231], v[28:31]
	v_mfma_f32_16x16x32_f16 v[24:27], v[184:187], v[228:231], v[24:27]
	v_mfma_f32_16x16x32_f16 v[12:15], v[176:179], v[236:239], v[12:15]
	v_mfma_f32_16x16x32_f16 v[8:11], v[184:187], v[236:239], v[8:11]
	s_setprio 0
	s_setprio 1
	v_mfma_f32_16x16x32_f16 v[52:55], v[188:191], v[204:207], v[52:55]
	v_mfma_f32_16x16x32_f16 v[48:51], v[196:199], v[204:207], v[48:51]
	v_mfma_f32_16x16x32_f16 v[36:39], v[188:191], v[212:215], v[36:39]
	v_mfma_f32_16x16x32_f16 v[32:35], v[196:199], v[212:215], v[32:35]
	v_mfma_f32_16x16x32_f16 v[20:23], v[188:191], v[220:223], v[20:23]
	v_mfma_f32_16x16x32_f16 v[16:19], v[196:199], v[220:223], v[16:19]
	v_mfma_f32_16x16x32_f16 v[4:7], v[188:191], v[232:235], v[4:7]
	v_mfma_f32_16x16x32_f16 v[0:3], v[196:199], v[232:235], v[0:3]
	v_mfma_f32_16x16x32_f16 v[52:55], v[192:195], v[208:211], v[52:55]
	v_mfma_f32_16x16x32_f16 v[48:51], v[200:203], v[208:211], v[48:51]
	v_mfma_f32_16x16x32_f16 v[36:39], v[192:195], v[216:219], v[36:39]
	v_mfma_f32_16x16x32_f16 v[32:35], v[200:203], v[216:219], v[32:35]
	v_mfma_f32_16x16x32_f16 v[20:23], v[192:195], v[228:231], v[20:23]
	v_mfma_f32_16x16x32_f16 v[16:19], v[200:203], v[228:231], v[16:19]
	v_mfma_f32_16x16x32_f16 v[4:7], v[192:195], v[236:239], v[4:7]
	v_mfma_f32_16x16x32_f16 v[0:3], v[200:203], v[236:239], v[0:3]
	s_setprio 0
	s_barrier
	s_add_i32 s74, s74, 2
	s_add_u32 s10, s10, 0x100
	s_addc_u32 s11, s11, 0
	s_add_u32 s72, s72, 0x100
	s_addc_u32 s73, s73, 0
	s_cmp_gt_u32 s74, 13

; #define PG8_STAGE(bufoff, gbase, voff) do { _Pragma("unroll") for (int _i = 0; _i < 2; ++_i) \
;         __builtin_amdgcn_global_load_lds((const unsigned*)((const char*)(gbase) + (voff)[_i]), (PG8_LAS unsigned*)(lds + (bufoff) + ldsw + _i * 8192), 16, 0, 0); } while (0)
; #define PG8_LDA(dst, b, h) do { _Pragma("unroll") for (int m = 0; m < 4; ++m) _Pragma("unroll") for (int k = 0; k < 2; ++k) dst[m][k] = *(const PG8_LAS bf16x8*)(lds + PG8_SA(b, h) + aoff + m * 2048 + k * 1024); } while (0)
; #define PG8_LDB(dst, b, h) do { _Pragma("unroll") for (int n = 0; n < 2; ++n) _Pragma("unroll") for (int k = 0; k < 2; ++k) dst[n][k] = *(const PG8_LAS bf16x8*)(lds + PG8_SB(b, h) + boff + n * 2048 + k * 1024); } while (0)
; #define PG8_WAIT_V(n) asm volatile("s_waitcnt vmcnt(" #n ")" ::: "memory")
; #define PG8_WAIT_L(n) asm volatile("s_waitcnt lgkmcnt(" #n ")" ::: "memory")
; #define PG8_BAR __builtin_amdgcn_s_barrier()
; #define PG8_SCHED __builtin_amdgcn_sched_barrier(0)
; template <class Epi, class Sched, bool ALIGN_EPI = false, bool SP2 = false, bool F16 = false, bool TOKPERM = false>
; __device__ __forceinline__ void gemm_phase(PG8_LAS unsigned char* lds, const Gemm g, const Sched& S, const Epi& E, int wv) {
;     ...
;         const bool has_next = S.next(ui + 1, nxt);
;         const char* nA = has_next ? (const char*)g.A + (size_t)nxt.pm * tstep : cA; const char* nB = has_next ? (const char*)g.Bt + (size_t)nxt.pn * tstep : cB;
;         for (int t = 0; t < nt; t += 2) {
;             const bool last = (t == nt - 2);
;             const char* a1 = cA + (size_t)(t + 1) * kstep;
;             const char* a2 = last ? nA : cA + (size_t)(t + 2) * kstep; const char* b2 = last ? nB : cB + (size_t)(t + 2) * kstep;
;             const char* a3 = a2 + kstep; const char* b3 = b2 + kstep;
;             if (last && has_next) S.a_ready(nxt);
;             if constexpr (SP2) {
;             PG8_LDB(B0, 0, 0); PG8_LDB(B1, 0, 1); PG8_SCHED; PG8_LDA(At, 0, 0); PG8_STAGE(PG8_SA(1, 1), a1 + hstep, voffA);
;             PG8_WAIT_V(8); PG8_WAIT_L(0); PG8_BAR; PG8_MMA(0, 0, At, B0); PG8_MMA(0, 1, At, B1); PG8_BAR; PG8_SCHED;
;             PG8_LDA(At, 0, 1); PG8_STAGE(PG8_SB(0, 0), b2, voffB); PG8_STAGE(PG8_SB(0, 1), b2 + hstep, voffB); PG8_STAGE(PG8_SA(0, 0), a2, voffA);
;             PG8_WAIT_V(8); PG8_WAIT_L(0); PG8_BAR; PG8_MMA(1, 0, At, B0); PG8_MMA(1, 1, At, B1); PG8_BAR; PG8_SCHED;
.LBB0_949:
	s_ashr_i32 s51, s50, 31
	s_lshl_b64 s[52:53], s[50:51], 19
	s_add_u32 s52, s40, s52
	s_addc_u32 s53, s41, s53
	s_and_b64 s[54:55], s[6:7], exec
	s_cselect_b32 s51, s53, s11
	s_cselect_b32 s70, s52, s10
	s_ashr_i32 s49, s48, 31
	s_lshl_b64 s[54:55], s[48:49], 19
	s_add_u32 s54, s0, s54
	s_addc_u32 s55, s1, s55
	s_and_b64 s[56:57], s[6:7], exec
	s_cselect_b32 s49, s55, s13
	s_cselect_b32 s71, s54, s12
	s_add_u32 s10, s10, 0x40080
	s_addc_u32 s11, s11, 0
	s_add_u32 s72, s12, 0x100
	s_addc_u32 s73, s13, 0
	s_mov_b32 s74, -2
	ds_read_b128 v[172:175], v155
	ds_read_b128 v[176:179], v156
	ds_read_b128 v[180:183], v157
	ds_read_b128 v[184:187], v158
	ds_read_b128 v[188:191], v159
	ds_read_b128 v[192:195], v160
	ds_read_b128 v[196:199], v161
	ds_read_b128 v[200:203], v162
	s_add_u32 s12, s10, 0xfffc0080
	s_addc_u32 s13, s11, -1
	s_cmp_eq_u32 s74, 12
	s_cselect_b32 s57, s51, s13
	s_cselect_b32 s56, s70, s12
	s_cselect_b32 s13, s49, s73
	s_cselect_b32 s12, s71, s72
	s_mov_b32 m0, s66
	v_lshl_add_u64 v[148:149], s[10:11], 0, v[140:141]
	ds_read_b128 v[204:207], v153
	ds_read_b128 v[208:211], v153 offset:1024
	ds_read_b128 v[212:215], v153 offset:2048
	ds_read_b128 v[216:219], v153 offset:3072
	ds_read_b128 v[220:223], v153 offset:4096
	ds_read_b128 v[228:231], v153 offset:5120
	ds_read_b128 v[232:235], v153 offset:6144
	ds_read_b128 v[236:239], v153 offset:7168
	global_load_lds_dwordx4 v[148:149], off
	v_lshl_add_u64 v[148:149], s[10:11], 0, v[142:143]
	s_mov_b32 m0, s67
	s_nop 0
	global_load_lds_dwordx4 v[148:149], off
	s_waitcnt vmcnt(8)
	s_waitcnt lgkmcnt(0)
	s_barrier
	s_setprio 1
	s_waitcnt lgkmcnt(0)
	v_mfma_f32_16x16x32_f16 v[124:127], v[172:175], v[204:207], 0
	v_mfma_f32_16x16x32_f16 v[116:119], v[180:183], v[204:207], 0
	v_mfma_f32_16x16x32_f16 v[108:111], v[172:175], v[212:215], 0
	v_mfma_f32_16x16x32_f16 v[104:107], v[180:183], v[212:215], 0
	v_mfma_f32_16x16x32_f16 v[92:95], v[172:175], v[220:223], 0
	v_mfma_f32_16x16x32_f16 v[88:91], v[180:183], v[220:223], 0
	v_mfma_f32_16x16x32_f16 v[76:79], v[172:175], v[232:235], 0
	v_mfma_f32_16x16x32_f16 v[72:75], v[180:183], v[232:235], 0
	v_mfma_f32_16x16x32_f16 v[124:127], v[176:179], v[208:211], v[124:127]
	v_mfma_f32_16x16x32_f16 v[116:119], v[184:187], v[208:211], v[116:119]
	v_mfma_f32_16x16x32_f16 v[108:111], v[176:179], v[216:219], v[108:111]
	v_mfma_f32_16x16x32_f16 v[104:107], v[184:187], v[216:219], v[104:107]
	v_mfma_f32_16x16x32_f16 v[92:95], v[176:179], v[228:231], v[92:95]
	v_mfma_f32_16x16x32_f16 v[88:91], v[184:187], v[228:231], v[88:91]
	v_mfma_f32_16x16x32_f16 v[76:79], v[176:179], v[236:239], v[76:79]
	v_mfma_f32_16x16x32_f16 v[72:75], v[184:187], v[236:239], v[72:75]
	s_setprio 0
	s_setprio 1
	v_mfma_f32_16x16x32_f16 v[120:123], v[188:191], v[204:207], 0
	v_mfma_f32_16x16x32_f16 v[112:115], v[196:199], v[204:207], 0
	v_mfma_f32_16x16x32_f16 v[100:103], v[188:191], v[212:215], 0
	v_mfma_f32_16x16x32_f16 v[96:99], v[196:199], v[212:215], 0
	v_mfma_f32_16x16x32_f16 v[84:87], v[188:191], v[220:223], 0
	v_mfma_f32_16x16x32_f16 v[80:83], v[196:199], v[220:223], 0
	v_mfma_f32_16x16x32_f16 v[68:71], v[188:191], v[232:235], 0
	v_mfma_f32_16x16x32_f16 v[64:67], v[196:199], v[232:235], 0
	v_mfma_f32_16x16x32_f16 v[120:123], v[192:195], v[208:211], v[120:123]
	v_mfma_f32_16x16x32_f16 v[112:115], v[200:203], v[208:211], v[112:115]
	v_mfma_f32_16x16x32_f16 v[100:103], v[192:195], v[216:219], v[100:103]
	v_mfma_f32_16x16x32_f16 v[96:99], v[200:203], v[216:219], v[96:99]
	v_mfma_f32_16x16x32_f16 v[84:87], v[192:195], v[228:231], v[84:87]
	v_mfma_f32_16x16x32_f16 v[80:83], v[200:203], v[228:231], v[80:83]
	v_mfma_f32_16x16x32_f16 v[68:71], v[192:195], v[236:239], v[68:71]
	v_mfma_f32_16x16x32_f16 v[64:67], v[200:203], v[236:239], v[64:67]
	s_setprio 0
	s_barrier
	s_mov_b32 m0, s5
	v_lshl_add_u64 v[148:149], s[12:13], 0, v[132:133]
	s_add_u32 s76, s12, 0x40000
	ds_read_b128 v[204:207], v153 offset:16384
	ds_read_b128 v[208:211], v153 offset:17408
	ds_read_b128 v[212:215], v153 offset:18432
	ds_read_b128 v[216:219], v153 offset:19456
	ds_read_b128 v[220:223], v153 offset:20480
	ds_read_b128 v[228:231], v153 offset:21504
	ds_read_b128 v[232:235], v153 offset:22528
	ds_read_b128 v[236:239], v153 offset:23552
	global_load_lds_dwordx4 v[148:149], off
	v_lshl_add_u64 v[224:225], s[12:13], 0, v[128:129]
	s_mov_b32 m0, s21
	s_addc_u32 s77, s13, 0
	global_load_lds_dwordx4 v[224:225], off
	v_lshl_add_u64 v[240:241], s[76:77], 0, v[132:133]
	s_mov_b32 m0, s23
	v_lshl_add_u64 v[242:243], s[56:57], 0, v[130:131]
	global_load_lds_dwordx4 v[240:241], off
	v_lshl_add_u64 v[240:241], s[76:77], 0, v[128:129]
	s_mov_b32 m0, s33
	s_nop 0
	global_load_lds_dwordx4 v[240:241], off
	v_lshl_add_u64 v[240:241], s[56:57], 0, v[134:135]
	s_mov_b32 m0, s2
	s_nop 0
	global_load_lds_dwordx4 v[240:241], off
	s_mov_b32 m0, s36
	s_nop 0
	global_load_lds_dwordx4 v[242:243], off
	s_waitcnt vmcnt(8)
	s_waitcnt lgkmcnt(0)
	s_barrier
; #define PG8_STAGE(bufoff, gbase, voff) do { _Pragma("unroll") for (int _i = 0; _i < 2; ++_i) \
;         __builtin_amdgcn_global_load_lds((const unsigned*)((const char*)(gbase) + (voff)[_i]), (PG8_LAS unsigned*)(lds + (bufoff) + ldsw + _i * 8192), 16, 0, 0); } while (0)
; #define PG8_LDA(dst, b, h) do { _Pragma("unroll") for (int m = 0; m < 4; ++m) _Pragma("unroll") for (int k = 0; k < 2; ++k) dst[m][k] = *(const PG8_LAS bf16x8*)(lds + PG8_SA(b, h) + aoff + m * 2048 + k * 1024); } while (0)
; #define PG8_LDB(dst, b, h) do { _Pragma("unroll") for (int n = 0; n < 2; ++n) _Pragma("unroll") for (int k = 0; k < 2; ++k) dst[n][k] = *(const PG8_LAS bf16x8*)(lds + PG8_SB(b, h) + boff + n * 2048 + k * 1024); } while (0)
; #define PG8_MMA(ai, bj, At, Bt) do { __builtin_amdgcn_s_setprio(1); _Pragma("unroll") for (int m = 0; m < 4; ++m) _Pragma("unroll") for (int n = 0; n < 2; ++n) _Pragma("unroll") for (int k = 0; k < 2; ++k) \
;         acc[ai][bj][m][n] = mma16<F16>(Bt[n][k], At[m][k], acc[ai][bj][m][n]); __builtin_amdgcn_s_setprio(0); } while (0)
; #define PG8_WAIT_V(n) asm volatile("s_waitcnt vmcnt(" #n ")" ::: "memory")
; #define PG8_WAIT_L(n) asm volatile("s_waitcnt lgkmcnt(" #n ")" ::: "memory")
; #define PG8_BAR __builtin_amdgcn_s_barrier()
; #define PG8_SCHED __builtin_amdgcn_sched_barrier(0)
; template <class Epi, class Sched, bool ALIGN_EPI = false, bool SP2 = false, bool F16 = false, bool TOKPERM = false>
; __device__ __forceinline__ void gemm_phase(PG8_LAS unsigned char* lds, const Gemm g, const Sched& S, const Epi& E, int wv) {
;     ...
;             PG8_WAIT_V(8); PG8_WAIT_L(0); PG8_BAR; PG8_MMA(1, 0, At, B0); PG8_MMA(1, 1, At, B1); PG8_BAR; PG8_SCHED;
;             PG8_LDB(B0, 1, 0); PG8_LDB(B1, 1, 1); PG8_SCHED; PG8_LDA(At, 1, 0); PG8_STAGE(PG8_SA(0, 1), a2 + hstep, voffA);
;             PG8_WAIT_V(8); PG8_WAIT_L(0); PG8_BAR; PG8_MMA(0, 0, At, B0); PG8_MMA(0, 1, At, B1); PG8_BAR; PG8_SCHED;
	s_setprio 1
	s_waitcnt lgkmcnt(0)
	v_mfma_f32_16x16x32_f16 v[60:63], v[172:175], v[204:207], 0
	v_mfma_f32_16x16x32_f16 v[56:59], v[180:183], v[204:207], 0
	v_mfma_f32_16x16x32_f16 v[44:47], v[172:175], v[212:215], 0
	v_mfma_f32_16x16x32_f16 v[40:43], v[180:183], v[212:215], 0
	v_mfma_f32_16x16x32_f16 v[28:31], v[172:175], v[220:223], 0
	v_mfma_f32_16x16x32_f16 v[24:27], v[180:183], v[220:223], 0
	v_mfma_f32_16x16x32_f16 v[12:15], v[172:175], v[232:235], 0
	v_mfma_f32_16x16x32_f16 v[8:11], v[180:183], v[232:235], 0
	v_mfma_f32_16x16x32_f16 v[60:63], v[176:179], v[208:211], v[60:63]
	v_mfma_f32_16x16x32_f16 v[56:59], v[184:187], v[208:211], v[56:59]
	v_mfma_f32_16x16x32_f16 v[44:47], v[176:179], v[216:219], v[44:47]
	v_mfma_f32_16x16x32_f16 v[40:43], v[184:187], v[216:219], v[40:43]
	v_mfma_f32_16x16x32_f16 v[28:31], v[176:179], v[228:231], v[28:31]
	v_mfma_f32_16x16x32_f16 v[24:27], v[184:187], v[228:231], v[24:27]
	v_mfma_f32_16x16x32_f16 v[12:15], v[176:179], v[236:239], v[12:15]
	v_mfma_f32_16x16x32_f16 v[8:11], v[184:187], v[236:239], v[8:11]
	s_setprio 0
	s_setprio 1
	v_mfma_f32_16x16x32_f16 v[52:55], v[188:191], v[204:207], 0
	v_mfma_f32_16x16x32_f16 v[48:51], v[196:199], v[204:207], 0
	v_mfma_f32_16x16x32_f16 v[36:39], v[188:191], v[212:215], 0
	v_mfma_f32_16x16x32_f16 v[32:35], v[196:199], v[212:215], 0
	v_mfma_f32_16x16x32_f16 v[20:23], v[188:191], v[220:223], 0
	v_mfma_f32_16x16x32_f16 v[16:19], v[196:199], v[220:223], 0
	v_mfma_f32_16x16x32_f16 v[4:7], v[188:191], v[232:235], 0
	v_mfma_f32_16x16x32_f16 v[0:3], v[196:199], v[232:235], 0
	v_mfma_f32_16x16x32_f16 v[52:55], v[192:195], v[208:211], v[52:55]
	v_mfma_f32_16x16x32_f16 v[48:51], v[200:203], v[208:211], v[48:51]
	v_mfma_f32_16x16x32_f16 v[36:39], v[192:195], v[216:219], v[36:39]
	v_mfma_f32_16x16x32_f16 v[32:35], v[200:203], v[216:219], v[32:35]
	v_mfma_f32_16x16x32_f16 v[20:23], v[192:195], v[228:231], v[20:23]
	v_mfma_f32_16x16x32_f16 v[16:19], v[200:203], v[228:231], v[16:19]
	v_mfma_f32_16x16x32_f16 v[4:7], v[192:195], v[236:239], v[4:7]
	v_mfma_f32_16x16x32_f16 v[0:3], v[200:203], v[236:239], v[0:3]
	s_setprio 0
	s_barrier
	ds_read_b128 v[172:175], v163
	ds_read_b128 v[176:179], v164
	ds_read_b128 v[180:183], v165
	ds_read_b128 v[184:187], v166
	ds_read_b128 v[188:191], v167
	ds_read_b128 v[192:195], v168
	ds_read_b128 v[196:199], v169
	ds_read_b128 v[200:203], v170
	s_add_u32 s56, s56, 0x40000
	s_addc_u32 s57, s57, 0
	s_mov_b32 m0, s37
	v_lshl_add_u64 v[244:245], s[56:57], 0, v[134:135]
	ds_read_b128 v[204:207], v153 offset:32768
	ds_read_b128 v[208:211], v153 offset:33792
	ds_read_b128 v[212:215], v153 offset:34816
	ds_read_b128 v[216:219], v153 offset:35840
	ds_read_b128 v[220:223], v153 offset:36864
	ds_read_b128 v[228:231], v153 offset:37888
	ds_read_b128 v[232:235], v153 offset:38912
	ds_read_b128 v[236:239], v153 offset:39936
	global_load_lds_dwordx4 v[244:245], off
	v_lshl_add_u64 v[244:245], s[56:57], 0, v[130:131]
	s_mov_b32 m0, s44
	s_nop 0
	global_load_lds_dwordx4 v[244:245], off
	s_waitcnt vmcnt(8)
	s_waitcnt lgkmcnt(0)
	s_barrier
	s_setprio 1
	s_waitcnt lgkmcnt(0)
	v_mfma_f32_16x16x32_f16 v[124:127], v[172:175], v[204:207], v[124:127]
	v_mfma_f32_16x16x32_f16 v[116:119], v[180:183], v[204:207], v[116:119]
	v_mfma_f32_16x16x32_f16 v[108:111], v[172:175], v[212:215], v[108:111]
	v_mfma_f32_16x16x32_f16 v[104:107], v[180:183], v[212:215], v[104:107]
	v_mfma_f32_16x16x32_f16 v[92:95], v[172:175], v[220:223], v[92:95]
	v_mfma_f32_16x16x32_f16 v[88:91], v[180:183], v[220:223], v[88:91]
	v_mfma_f32_16x16x32_f16 v[76:79], v[172:175], v[232:235], v[76:79]
	v_mfma_f32_16x16x32_f16 v[72:75], v[180:183], v[232:235], v[72:75]
	v_mfma_f32_16x16x32_f16 v[124:127], v[176:179], v[208:211], v[124:127]
	v_mfma_f32_16x16x32_f16 v[116:119], v[184:187], v[208:211], v[116:119]
	v_mfma_f32_16x16x32_f16 v[108:111], v[176:179], v[216:219], v[108:111]
	v_mfma_f32_16x16x32_f16 v[104:107], v[184:187], v[216:219], v[104:107]
	v_mfma_f32_16x16x32_f16 v[92:95], v[176:179], v[228:231], v[92:95]
	v_mfma_f32_16x16x32_f16 v[88:91], v[184:187], v[228:231], v[88:91]
	v_mfma_f32_16x16x32_f16 v[76:79], v[176:179], v[236:239], v[76:79]
	v_mfma_f32_16x16x32_f16 v[72:75], v[184:187], v[236:239], v[72:75]
	s_setprio 0
	s_setprio 1
	v_mfma_f32_16x16x32_f16 v[120:123], v[188:191], v[204:207], v[120:123]
	v_mfma_f32_16x16x32_f16 v[112:115], v[196:199], v[204:207], v[112:115]
	v_mfma_f32_16x16x32_f16 v[100:103], v[188:191], v[212:215], v[100:103]
	v_mfma_f32_16x16x32_f16 v[96:99], v[196:199], v[212:215], v[96:99]
	v_mfma_f32_16x16x32_f16 v[84:87], v[188:191], v[220:223], v[84:87]
	v_mfma_f32_16x16x32_f16 v[80:83], v[196:199], v[220:223], v[80:83]
	v_mfma_f32_16x16x32_f16 v[68:71], v[188:191], v[232:235], v[68:71]
	v_mfma_f32_16x16x32_f16 v[64:67], v[196:199], v[232:235], v[64:67]
	v_mfma_f32_16x16x32_f16 v[120:123], v[192:195], v[208:211], v[120:123]
	v_mfma_f32_16x16x32_f16 v[112:115], v[200:203], v[208:211], v[112:115]
	v_mfma_f32_16x16x32_f16 v[100:103], v[192:195], v[216:219], v[100:103]
	v_mfma_f32_16x16x32_f16 v[96:99], v[200:203], v[216:219], v[96:99]
	v_mfma_f32_16x16x32_f16 v[84:87], v[192:195], v[228:231], v[84:87]
	v_mfma_f32_16x16x32_f16 v[80:83], v[200:203], v[228:231], v[80:83]
	v_mfma_f32_16x16x32_f16 v[68:71], v[192:195], v[236:239], v[68:71]
	v_mfma_f32_16x16x32_f16 v[64:67], v[200:203], v[236:239], v[64:67]
	s_setprio 0
	s_barrier
; #define PG8_STAGE(bufoff, gbase, voff) do { _Pragma("unroll") for (int _i = 0; _i < 2; ++_i) \
;         __builtin_amdgcn_global_load_lds((const unsigned*)((const char*)(gbase) + (voff)[_i]), (PG8_LAS unsigned*)(lds + (bufoff) + ldsw + _i * 8192), 16, 0, 0); } while (0)
; #define PG8_LDA(dst, b, h) do { _Pragma("unroll") for (int m = 0; m < 4; ++m) _Pragma("unroll") for (int k = 0; k < 2; ++k) dst[m][k] = *(const PG8_LAS bf16x8*)(lds + PG8_SA(b, h) + aoff + m * 2048 + k * 1024); } while (0)
; #define PG8_MMA(ai, bj, At, Bt) do { __builtin_amdgcn_s_setprio(1); _Pragma("unroll") for (int m = 0; m < 4; ++m) _Pragma("unroll") for (int n = 0; n < 2; ++n) _Pragma("unroll") for (int k = 0; k < 2; ++k) \
;         acc[ai][bj][m][n] = mma16<F16>(Bt[n][k], At[m][k], acc[ai][bj][m][n]); __builtin_amdgcn_s_setprio(0); } while (0)
; #define PG8_WAIT_V(n) asm volatile("s_waitcnt vmcnt(" #n ")" ::: "memory")
; #define PG8_WAIT_L(n) asm volatile("s_waitcnt lgkmcnt(" #n ")" ::: "memory")
; #define PG8_BAR __builtin_amdgcn_s_barrier()
; #define PG8_SCHED __builtin_amdgcn_sched_barrier(0)
; template <class Epi, class Sched, bool ALIGN_EPI = false, bool SP2 = false, bool F16 = false, bool TOKPERM = false>
; __device__ __forceinline__ void gemm_phase(PG8_LAS unsigned char* lds, const Gemm g, const Sched& S, const Epi& E, int wv) {
;     ...
;             PG8_LDA(At, 1, 1); PG8_STAGE(PG8_SB(1, 0), b3, voffB); PG8_STAGE(PG8_SB(1, 1), b3 + hstep, voffB); PG8_STAGE(PG8_SA(1, 0), a3, voffA);
;             PG8_WAIT_V(8); PG8_WAIT_L(0); PG8_BAR; PG8_MMA(1, 0, At, B0); PG8_MMA(1, 1, At, B1); PG8_BAR; PG8_SCHED;
	s_mov_b32 m0, s58
	v_lshl_add_u64 v[148:149], v[148:149], 0, s[16:17]
	s_add_u32 s12, s12, 0x40080
	ds_read_b128 v[204:207], v153 offset:49152
	ds_read_b128 v[208:211], v153 offset:50176
	ds_read_b128 v[212:215], v153 offset:51200
	ds_read_b128 v[216:219], v153 offset:52224
	ds_read_b128 v[220:223], v153 offset:53248
	ds_read_b128 v[228:231], v153 offset:54272
	ds_read_b128 v[232:235], v153 offset:55296
	ds_read_b128 v[236:239], v153 offset:56320
	global_load_lds_dwordx4 v[148:149], off
	v_lshl_add_u64 v[148:149], v[224:225], 0, s[16:17]
	s_mov_b32 m0, s59
	s_addc_u32 s13, s13, 0
	global_load_lds_dwordx4 v[148:149], off
	v_lshl_add_u64 v[148:149], s[12:13], 0, v[132:133]
	s_mov_b32 m0, s62
	s_nop 0
	global_load_lds_dwordx4 v[148:149], off
	v_lshl_add_u64 v[148:149], s[12:13], 0, v[128:129]
	s_mov_b32 m0, s63
	s_nop 0
	global_load_lds_dwordx4 v[148:149], off
	v_lshl_add_u64 v[148:149], v[240:241], 0, s[16:17]
	s_mov_b32 m0, s60
	s_nop 0
	global_load_lds_dwordx4 v[148:149], off
	v_lshl_add_u64 v[148:149], v[242:243], 0, s[16:17]
	s_mov_b32 m0, s61
	s_nop 0
	global_load_lds_dwordx4 v[148:149], off
	s_waitcnt vmcnt(8)
	s_waitcnt lgkmcnt(0)
	s_barrier
	s_setprio 1
	s_waitcnt lgkmcnt(0)
	v_mfma_f32_16x16x32_f16 v[60:63], v[172:175], v[204:207], v[60:63]
	v_mfma_f32_16x16x32_f16 v[56:59], v[180:183], v[204:207], v[56:59]
	v_mfma_f32_16x16x32_f16 v[44:47], v[172:175], v[212:215], v[44:47]
	v_mfma_f32_16x16x32_f16 v[40:43], v[180:183], v[212:215], v[40:43]
	v_mfma_f32_16x16x32_f16 v[28:31], v[172:175], v[220:223], v[28:31]
	v_mfma_f32_16x16x32_f16 v[24:27], v[180:183], v[220:223], v[24:27]
	v_mfma_f32_16x16x32_f16 v[12:15], v[172:175], v[232:235], v[12:15]
	v_mfma_f32_16x16x32_f16 v[8:11], v[180:183], v[232:235], v[8:11]
	v_mfma_f32_16x16x32_f16 v[60:63], v[176:179], v[208:211], v[60:63]
	v_mfma_f32_16x16x32_f16 v[56:59], v[184:187], v[208:211], v[56:59]
	v_mfma_f32_16x16x32_f16 v[44:47], v[176:179], v[216:219], v[44:47]
	v_mfma_f32_16x16x32_f16 v[40:43], v[184:187], v[216:219], v[40:43]
	v_mfma_f32_16x16x32_f16 v[28:31], v[176:179], v[228:231], v[28:31]
	v_mfma_f32_16x16x32_f16 v[24:27], v[184:187], v[228:231], v[24:27]
	v_mfma_f32_16x16x32_f16 v[12:15], v[176:179], v[236:239], v[12:15]
	v_mfma_f32_16x16x32_f16 v[8:11], v[184:187], v[236:239], v[8:11]
	s_setprio 0
	s_setprio 1
	v_mfma_f32_16x16x32_f16 v[52:55], v[188:191], v[204:207], v[52:55]
	v_mfma_f32_16x16x32_f16 v[48:51], v[196:199], v[204:207], v[48:51]
	v_mfma_f32_16x16x32_f16 v[36:39], v[188:191], v[212:215], v[36:39]
	v_mfma_f32_16x16x32_f16 v[32:35], v[196:199], v[212:215], v[32:35]
	v_mfma_f32_16x16x32_f16 v[20:23], v[188:191], v[220:223], v[20:23]
	v_mfma_f32_16x16x32_f16 v[16:19], v[196:199], v[220:223], v[16:19]
	v_mfma_f32_16x16x32_f16 v[4:7], v[188:191], v[232:235], v[4:7]
	v_mfma_f32_16x16x32_f16 v[0:3], v[196:199], v[232:235], v[0:3]
	v_mfma_f32_16x16x32_f16 v[52:55], v[192:195], v[208:211], v[52:55]
	v_mfma_f32_16x16x32_f16 v[48:51], v[200:203], v[208:211], v[48:51]
	v_mfma_f32_16x16x32_f16 v[36:39], v[192:195], v[216:219], v[36:39]
	v_mfma_f32_16x16x32_f16 v[32:35], v[200:203], v[216:219], v[32:35]
	v_mfma_f32_16x16x32_f16 v[20:23], v[192:195], v[228:231], v[20:23]
	v_mfma_f32_16x16x32_f16 v[16:19], v[200:203], v[228:231], v[16:19]
	v_mfma_f32_16x16x32_f16 v[4:7], v[192:195], v[236:239], v[4:7]
	v_mfma_f32_16x16x32_f16 v[0:3], v[200:203], v[236:239], v[0:3]
	s_setprio 0
	s_barrier
	s_add_i32 s74, s74, 2
	s_add_u32 s10, s10, 0x100
	s_addc_u32 s11, s11, 0
	s_add_u32 s72, s72, 0x100
	s_addc_u32 s73, s73, 0
	s_cmp_gt_u32 s74, 13

; #define PG8_STAGE(bufoff, gbase, voff) do { _Pragma("unroll") for (int _i = 0; _i < 2; ++_i) \
;         __builtin_amdgcn_global_load_lds((const unsigned*)((const char*)(gbase) + (voff)[_i]), (PG8_LAS unsigned*)(lds + (bufoff) + ldsw + _i * 8192), 16, 0, 0); } while (0)
; #define PG8_LDA(dst, b, h) do { _Pragma("unroll") for (int m = 0; m < 4; ++m) _Pragma("unroll") for (int k = 0; k < 2; ++k) dst[m][k] = *(const PG8_LAS bf16x8*)(lds + PG8_SA(b, h) + aoff + m * 2048 + k * 1024); } while (0)
; #define PG8_LDB(dst, b, h) do { _Pragma("unroll") for (int n = 0; n < 2; ++n) _Pragma("unroll") for (int k = 0; k < 2; ++k) dst[n][k] = *(const PG8_LAS bf16x8*)(lds + PG8_SB(b, h) + boff + n * 2048 + k * 1024); } while (0)
; #define PG8_WAIT_V(n) asm volatile("s_waitcnt vmcnt(" #n ")" ::: "memory")
; #define PG8_WAIT_L(n) asm volatile("s_waitcnt lgkmcnt(" #n ")" ::: "memory")
; #define PG8_BAR __builtin_amdgcn_s_barrier()
; #define PG8_SCHED __builtin_amdgcn_sched_barrier(0)
; template <class Epi, class Sched, bool ALIGN_EPI = false, bool SP2 = false, bool F16 = false, bool TOKPERM = false>
; __device__ __forceinline__ void gemm_phase(PG8_LAS unsigned char* lds, const Gemm g, const Sched& S, const Epi& E, int wv) {
;     ...
;         const bool has_next = S.next(ui + 1, nxt);
;         const char* nA = has_next ? (const char*)g.A + (size_t)nxt.pm * tstep : cA; const char* nB = has_next ? (const char*)g.Bt + (size_t)nxt.pn * tstep : cB;
;         for (int t = 0; t < nt; t += 2) {
;             const bool last = (t == nt - 2);
;             const char* a1 = cA + (size_t)(t + 1) * kstep;
;             const char* a2 = last ? nA : cA + (size_t)(t + 2) * kstep; const char* b2 = last ? nB : cB + (size_t)(t + 2) * kstep;
;             const char* a3 = a2 + kstep; const char* b3 = b2 + kstep;
;             if (last && has_next) S.a_ready(nxt);
;             if constexpr (SP2) {
;             PG8_LDB(B0, 0, 0); PG8_LDB(B1, 0, 1); PG8_SCHED; PG8_LDA(At, 0, 0); PG8_STAGE(PG8_SA(1, 1), a1 + hstep, voffA);
;             PG8_WAIT_V(8); PG8_WAIT_L(0); PG8_BAR; PG8_MMA(0, 0, At, B0); PG8_MMA(0, 1, At, B1); PG8_BAR; PG8_SCHED;
;             PG8_LDA(At, 0, 1); PG8_STAGE(PG8_SB(0, 0), b2, voffB); PG8_STAGE(PG8_SB(0, 1), b2 + hstep, voffB); PG8_STAGE(PG8_SA(0, 0), a2, voffA);
;             PG8_WAIT_V(8); PG8_WAIT_L(0); PG8_BAR; PG8_MMA(1, 0, At, B0); PG8_MMA(1, 1, At, B1); PG8_BAR; PG8_SCHED;
.LBB0_1117:
	s_ashr_i32 s79, s78, 31
	s_lshl_b64 s[14:15], s[78:79], 19
	s_add_u32 s80, s40, s14
	s_addc_u32 s81, s41, s15
	s_and_b64 s[14:15], s[6:7], exec
	s_cselect_b32 s9, s81, s11
	s_cselect_b32 s18, s80, s10
	s_ashr_i32 s77, s76, 31
	s_lshl_b64 s[14:15], s[76:77], 19
	s_add_u32 s82, s0, s14
	s_addc_u32 s83, s1, s15
	s_and_b64 s[14:15], s[6:7], exec
	s_cselect_b32 s19, s83, s13
	s_cselect_b32 s58, s82, s12
	s_add_u32 s59, s12, 0x100
	s_addc_u32 s62, s13, 0
	s_mov_b32 s63, -2
	s_waitcnt lgkmcnt(0)
	ds_read_b128 v[128:131], v190
	ds_read_b128 v[132:135], v191
	ds_read_b128 v[154:157], v192
	ds_read_b128 v[158:161], v193
	ds_read_b128 v[162:165], v194
	ds_read_b128 v[166:169], v195
	ds_read_b128 v[170:173], v196
	ds_read_b128 v[174:177], v197
	s_add_u32 s12, s10, 0x100
	s_addc_u32 s13, s11, 0
	s_cmp_eq_u32 s63, 12
	s_cselect_b32 s17, s9, s13
	s_cselect_b32 s16, s18, s12
	s_cselect_b32 s15, s19, s62
	s_cselect_b32 s14, s58, s59
	s_mov_b32 m0, s22
	v_lshl_add_u64 v[236:237], s[10:11], 0, v[146:147]
	ds_read_b128 v[178:181], v187
	ds_read_b128 v[182:185], v187 offset:1024
	ds_read_b128 v[210:213], v187 offset:2048
	ds_read_b128 v[214:217], v187 offset:3072
	ds_read_b128 v[218:221], v187 offset:4096
	ds_read_b128 v[222:225], v187 offset:5120
	ds_read_b128 v[228:231], v187 offset:6144
	ds_read_b128 v[232:235], v187 offset:7168
	global_load_lds_dwordx4 v[236:237], off
	v_lshl_add_u64 v[236:237], s[10:11], 0, v[148:149]
	s_mov_b32 m0, s23
	s_nop 0
	global_load_lds_dwordx4 v[236:237], off
	s_waitcnt vmcnt(8)
	s_waitcnt lgkmcnt(0)
	s_barrier
	s_setprio 1
	s_waitcnt lgkmcnt(0)
	v_mfma_f32_16x16x32_f16 v[124:127], v[128:131], v[178:181], 0
	v_mfma_f32_16x16x32_f16 v[108:111], v[154:157], v[178:181], 0
	v_mfma_f32_16x16x32_f16 v[120:123], v[128:131], v[210:213], 0
	v_mfma_f32_16x16x32_f16 v[104:107], v[154:157], v[210:213], 0
	v_mfma_f32_16x16x32_f16 v[116:119], v[128:131], v[218:221], 0
	v_mfma_f32_16x16x32_f16 v[100:103], v[154:157], v[218:221], 0
	v_mfma_f32_16x16x32_f16 v[112:115], v[128:131], v[228:231], 0
	v_mfma_f32_16x16x32_f16 v[96:99], v[154:157], v[228:231], 0
	v_mfma_f32_16x16x32_f16 v[124:127], v[132:135], v[182:185], v[124:127]
	v_mfma_f32_16x16x32_f16 v[108:111], v[158:161], v[182:185], v[108:111]
	v_mfma_f32_16x16x32_f16 v[120:123], v[132:135], v[214:217], v[120:123]
	v_mfma_f32_16x16x32_f16 v[104:107], v[158:161], v[214:217], v[104:107]
	v_mfma_f32_16x16x32_f16 v[116:119], v[132:135], v[222:225], v[116:119]
	v_mfma_f32_16x16x32_f16 v[100:103], v[158:161], v[222:225], v[100:103]
	v_mfma_f32_16x16x32_f16 v[112:115], v[132:135], v[232:235], v[112:115]
	v_mfma_f32_16x16x32_f16 v[96:99], v[158:161], v[232:235], v[96:99]
	s_setprio 0
	s_setprio 1
	v_mfma_f32_16x16x32_f16 v[92:95], v[162:165], v[178:181], 0
	v_mfma_f32_16x16x32_f16 v[76:79], v[170:173], v[178:181], 0
	v_mfma_f32_16x16x32_f16 v[88:91], v[162:165], v[210:213], 0
	v_mfma_f32_16x16x32_f16 v[72:75], v[170:173], v[210:213], 0
	v_mfma_f32_16x16x32_f16 v[84:87], v[162:165], v[218:221], 0
	v_mfma_f32_16x16x32_f16 v[68:71], v[170:173], v[218:221], 0
	v_mfma_f32_16x16x32_f16 v[80:83], v[162:165], v[228:231], 0
	v_mfma_f32_16x16x32_f16 v[64:67], v[170:173], v[228:231], 0
	v_mfma_f32_16x16x32_f16 v[92:95], v[166:169], v[182:185], v[92:95]
	v_mfma_f32_16x16x32_f16 v[76:79], v[174:177], v[182:185], v[76:79]
	v_mfma_f32_16x16x32_f16 v[88:91], v[166:169], v[214:217], v[88:91]
	v_mfma_f32_16x16x32_f16 v[72:75], v[174:177], v[214:217], v[72:75]
	v_mfma_f32_16x16x32_f16 v[84:87], v[166:169], v[222:225], v[84:87]
	v_mfma_f32_16x16x32_f16 v[68:71], v[174:177], v[222:225], v[68:71]
	v_mfma_f32_16x16x32_f16 v[80:83], v[166:169], v[232:235], v[80:83]
	v_mfma_f32_16x16x32_f16 v[64:67], v[174:177], v[232:235], v[64:67]
	s_setprio 0
	s_barrier
	s_mov_b32 m0, s3
	v_lshl_add_u64 v[236:237], s[14:15], 0, v[138:139]
	s_add_u32 s10, s14, 0x40000
	ds_read_b128 v[178:181], v187 offset:16384
	ds_read_b128 v[182:185], v187 offset:17408
	ds_read_b128 v[210:213], v187 offset:18432
	ds_read_b128 v[214:217], v187 offset:19456
	ds_read_b128 v[218:221], v187 offset:20480
	ds_read_b128 v[222:225], v187 offset:21504
	ds_read_b128 v[228:231], v187 offset:22528
	ds_read_b128 v[232:235], v187 offset:23552
	global_load_lds_dwordx4 v[236:237], off
	v_lshl_add_u64 v[238:239], s[14:15], 0, v[142:143]
	s_mov_b32 m0, s33
	s_addc_u32 s11, s15, 0
	global_load_lds_dwordx4 v[238:239], off
	v_lshl_add_u64 v[240:241], s[10:11], 0, v[138:139]
	s_mov_b32 m0, s36
	v_lshl_add_u64 v[242:243], s[16:17], 0, v[140:141]
	global_load_lds_dwordx4 v[240:241], off
	v_lshl_add_u64 v[240:241], s[10:11], 0, v[142:143]
	s_mov_b32 m0, s37
	s_nop 0
	global_load_lds_dwordx4 v[240:241], off
	v_lshl_add_u64 v[240:241], s[16:17], 0, v[136:137]
	s_mov_b32 m0, s2
	s_nop 0
	global_load_lds_dwordx4 v[240:241], off
	s_mov_b32 m0, s44
	s_nop 0
	global_load_lds_dwordx4 v[242:243], off
	s_waitcnt vmcnt(8)
	s_waitcnt lgkmcnt(0)
	s_barrier
; #define PG8_STAGE(bufoff, gbase, voff) do { _Pragma("unroll") for (int _i = 0; _i < 2; ++_i) \
;         __builtin_amdgcn_global_load_lds((const unsigned*)((const char*)(gbase) + (voff)[_i]), (PG8_LAS unsigned*)(lds + (bufoff) + ldsw + _i * 8192), 16, 0, 0); } while (0)
; #define PG8_LDA(dst, b, h) do { _Pragma("unroll") for (int m = 0; m < 4; ++m) _Pragma("unroll") for (int k = 0; k < 2; ++k) dst[m][k] = *(const PG8_LAS bf16x8*)(lds + PG8_SA(b, h) + aoff + m * 2048 + k * 1024); } while (0)
; #define PG8_LDB(dst, b, h) do { _Pragma("unroll") for (int n = 0; n < 2; ++n) _Pragma("unroll") for (int k = 0; k < 2; ++k) dst[n][k] = *(const PG8_LAS bf16x8*)(lds + PG8_SB(b, h) + boff + n * 2048 + k * 1024); } while (0)
; #define PG8_MMA(ai, bj, At, Bt) do { __builtin_amdgcn_s_setprio(1); _Pragma("unroll") for (int m = 0; m < 4; ++m) _Pragma("unroll") for (int n = 0; n < 2; ++n) _Pragma("unroll") for (int k = 0; k < 2; ++k) \
;         acc[ai][bj][m][n] = mma16<F16>(Bt[n][k], At[m][k], acc[ai][bj][m][n]); __builtin_amdgcn_s_setprio(0); } while (0)
; #define PG8_BAR __builtin_amdgcn_s_barrier()
; template <class Epi, class Sched, bool ALIGN_EPI = false, bool SP2 = false, bool F16 = false, bool TOKPERM = false>
; __device__ __forceinline__ void gemm_phase(PG8_LAS unsigned char* lds, const Gemm g, const Sched& S, const Epi& E, int wv) {
;     ...
;             PG8_LDB(B0, 0, 0); PG8_LDB(B1, 0, 1); PG8_SCHED; PG8_LDA(At, 0, 0); PG8_STAGE(PG8_SA(1, 1), a1 + hstep, voffA);
;             PG8_WAIT_V(8); PG8_WAIT_L(0); PG8_BAR; PG8_MMA(0, 0, At, B0); PG8_MMA(0, 1, At, B1); PG8_BAR; PG8_SCHED;
;             PG8_LDA(At, 0, 1); PG8_STAGE(PG8_SB(0, 0), b2, voffB); PG8_STAGE(PG8_SB(0, 1), b2 + hstep, voffB); PG8_STAGE(PG8_SA(0, 0), a2, voffA);
;             PG8_WAIT_V(8); PG8_WAIT_L(0); PG8_BAR; PG8_MMA(1, 0, At, B0); PG8_MMA(1, 1, At, B1); PG8_BAR; PG8_SCHED;
;             PG8_LDB(B0, 1, 0); PG8_LDB(B1, 1, 1); PG8_SCHED; PG8_LDA(At, 1, 0); PG8_STAGE(PG8_SA(0, 1), a2 + hstep, voffA);
;             PG8_WAIT_V(8); PG8_WAIT_L(0); PG8_BAR; PG8_MMA(0, 0, At, B0); PG8_MMA(0, 1, At, B1); PG8_BAR; PG8_SCHED;
;             PG8_LDA(At, 1, 1); PG8_STAGE(PG8_SB(1, 0), b3, voffB); PG8_STAGE(PG8_SB(1, 1), b3 + hstep, voffB); PG8_STAGE(PG8_SA(1, 0), a3, voffA);
;             PG8_WAIT_V(8); PG8_WAIT_L(0); PG8_BAR; PG8_MMA(1, 0, At, B0); PG8_MMA(1, 1, At, B1); PG8_BAR; PG8_SCHED;
	s_setprio 1
	s_waitcnt lgkmcnt(0)
	v_mfma_f32_16x16x32_f16 v[60:63], v[128:131], v[178:181], 0
	v_mfma_f32_16x16x32_f16 v[44:47], v[154:157], v[178:181], 0
	v_mfma_f32_16x16x32_f16 v[56:59], v[128:131], v[210:213], 0
	v_mfma_f32_16x16x32_f16 v[40:43], v[154:157], v[210:213], 0
	v_mfma_f32_16x16x32_f16 v[52:55], v[128:131], v[218:221], 0
	v_mfma_f32_16x16x32_f16 v[36:39], v[154:157], v[218:221], 0
	v_mfma_f32_16x16x32_f16 v[48:51], v[128:131], v[228:231], 0
	v_mfma_f32_16x16x32_f16 v[32:35], v[154:157], v[228:231], 0
	v_mfma_f32_16x16x32_f16 v[60:63], v[132:135], v[182:185], v[60:63]
	v_mfma_f32_16x16x32_f16 v[44:47], v[158:161], v[182:185], v[44:47]
	v_mfma_f32_16x16x32_f16 v[56:59], v[132:135], v[214:217], v[56:59]
	v_mfma_f32_16x16x32_f16 v[40:43], v[158:161], v[214:217], v[40:43]
	v_mfma_f32_16x16x32_f16 v[52:55], v[132:135], v[222:225], v[52:55]
	v_mfma_f32_16x16x32_f16 v[36:39], v[158:161], v[222:225], v[36:39]
	v_mfma_f32_16x16x32_f16 v[48:51], v[132:135], v[232:235], v[48:51]
	v_mfma_f32_16x16x32_f16 v[32:35], v[158:161], v[232:235], v[32:35]
	s_setprio 0
	s_setprio 1
	v_mfma_f32_16x16x32_f16 v[28:31], v[162:165], v[178:181], 0
	v_mfma_f32_16x16x32_f16 v[12:15], v[170:173], v[178:181], 0
	v_mfma_f32_16x16x32_f16 v[24:27], v[162:165], v[210:213], 0
	v_mfma_f32_16x16x32_f16 v[8:11], v[170:173], v[210:213], 0
	v_mfma_f32_16x16x32_f16 v[20:23], v[162:165], v[218:221], 0
	v_mfma_f32_16x16x32_f16 v[4:7], v[170:173], v[218:221], 0
	v_mfma_f32_16x16x32_f16 v[16:19], v[162:165], v[228:231], 0
	v_mfma_f32_16x16x32_f16 v[0:3], v[170:173], v[228:231], 0
	v_mfma_f32_16x16x32_f16 v[28:31], v[166:169], v[182:185], v[28:31]
	v_mfma_f32_16x16x32_f16 v[12:15], v[174:177], v[182:185], v[12:15]
	v_mfma_f32_16x16x32_f16 v[24:27], v[166:169], v[214:217], v[24:27]
	v_mfma_f32_16x16x32_f16 v[8:11], v[174:177], v[214:217], v[8:11]
	v_mfma_f32_16x16x32_f16 v[20:23], v[166:169], v[222:225], v[20:23]
	v_mfma_f32_16x16x32_f16 v[4:7], v[174:177], v[222:225], v[4:7]
	v_mfma_f32_16x16x32_f16 v[16:19], v[166:169], v[232:235], v[16:19]
	v_mfma_f32_16x16x32_f16 v[0:3], v[174:177], v[232:235], v[0:3]
	s_setprio 0
	s_barrier
	ds_read_b128 v[128:131], v198
	ds_read_b128 v[132:135], v199
	ds_read_b128 v[154:157], v200
	ds_read_b128 v[158:161], v201
	ds_read_b128 v[162:165], v202
	ds_read_b128 v[166:169], v203
	ds_read_b128 v[170:173], v204
	ds_read_b128 v[174:177], v205
	s_add_u32 s10, s16, 0x40000
	s_addc_u32 s11, s17, 0
	s_mov_b32 m0, s45
	v_lshl_add_u64 v[244:245], s[10:11], 0, v[136:137]
	ds_read_b128 v[178:181], v187 offset:32768
	ds_read_b128 v[182:185], v187 offset:33792
	ds_read_b128 v[210:213], v187 offset:34816
	ds_read_b128 v[214:217], v187 offset:35840
	ds_read_b128 v[218:221], v187 offset:36864
	ds_read_b128 v[222:225], v187 offset:37888
	ds_read_b128 v[228:231], v187 offset:38912
	ds_read_b128 v[232:235], v187 offset:39936
	global_load_lds_dwordx4 v[244:245], off
	v_lshl_add_u64 v[244:245], s[10:11], 0, v[140:141]
	s_mov_b32 m0, s61
	s_nop 0
	global_load_lds_dwordx4 v[244:245], off
	s_waitcnt vmcnt(8)
	s_waitcnt lgkmcnt(0)
	s_barrier
	s_setprio 1
	s_waitcnt lgkmcnt(0)
	v_mfma_f32_16x16x32_f16 v[124:127], v[128:131], v[178:181], v[124:127]
	v_mfma_f32_16x16x32_f16 v[108:111], v[154:157], v[178:181], v[108:111]
	v_mfma_f32_16x16x32_f16 v[120:123], v[128:131], v[210:213], v[120:123]
	v_mfma_f32_16x16x32_f16 v[104:107], v[154:157], v[210:213], v[104:107]
	v_mfma_f32_16x16x32_f16 v[116:119], v[128:131], v[218:221], v[116:119]
	v_mfma_f32_16x16x32_f16 v[100:103], v[154:157], v[218:221], v[100:103]
	v_mfma_f32_16x16x32_f16 v[112:115], v[128:131], v[228:231], v[112:115]
	v_mfma_f32_16x16x32_f16 v[96:99], v[154:157], v[228:231], v[96:99]
	v_mfma_f32_16x16x32_f16 v[124:127], v[132:135], v[182:185], v[124:127]
	v_mfma_f32_16x16x32_f16 v[108:111], v[158:161], v[182:185], v[108:111]
	v_mfma_f32_16x16x32_f16 v[120:123], v[132:135], v[214:217], v[120:123]
	v_mfma_f32_16x16x32_f16 v[104:107], v[158:161], v[214:217], v[104:107]
	v_mfma_f32_16x16x32_f16 v[116:119], v[132:135], v[222:225], v[116:119]
	v_mfma_f32_16x16x32_f16 v[100:103], v[158:161], v[222:225], v[100:103]
	v_mfma_f32_16x16x32_f16 v[112:115], v[132:135], v[232:235], v[112:115]
	v_mfma_f32_16x16x32_f16 v[96:99], v[158:161], v[232:235], v[96:99]
	s_setprio 0
	s_setprio 1
	v_mfma_f32_16x16x32_f16 v[92:95], v[162:165], v[178:181], v[92:95]
	v_mfma_f32_16x16x32_f16 v[76:79], v[170:173], v[178:181], v[76:79]
	v_mfma_f32_16x16x32_f16 v[88:91], v[162:165], v[210:213], v[88:91]
	v_mfma_f32_16x16x32_f16 v[72:75], v[170:173], v[210:213], v[72:75]
	v_mfma_f32_16x16x32_f16 v[84:87], v[162:165], v[218:221], v[84:87]
	v_mfma_f32_16x16x32_f16 v[68:71], v[170:173], v[218:221], v[68:71]
	v_mfma_f32_16x16x32_f16 v[80:83], v[162:165], v[228:231], v[80:83]
	v_mfma_f32_16x16x32_f16 v[64:67], v[170:173], v[228:231], v[64:67]
	v_mfma_f32_16x16x32_f16 v[92:95], v[166:169], v[182:185], v[92:95]
	v_mfma_f32_16x16x32_f16 v[76:79], v[174:177], v[182:185], v[76:79]
	v_mfma_f32_16x16x32_f16 v[88:91], v[166:169], v[214:217], v[88:91]
	v_mfma_f32_16x16x32_f16 v[72:75], v[174:177], v[214:217], v[72:75]
	v_mfma_f32_16x16x32_f16 v[84:87], v[166:169], v[222:225], v[84:87]
	v_mfma_f32_16x16x32_f16 v[68:71], v[174:177], v[222:225], v[68:71]
	v_mfma_f32_16x16x32_f16 v[80:83], v[166:169], v[232:235], v[80:83]
	v_mfma_f32_16x16x32_f16 v[64:67], v[174:177], v[232:235], v[64:67]
	s_setprio 0
	s_barrier
; #define PG8_STAGE(bufoff, gbase, voff) do { _Pragma("unroll") for (int _i = 0; _i < 2; ++_i) \
;         __builtin_amdgcn_global_load_lds((const unsigned*)((const char*)(gbase) + (voff)[_i]), (PG8_LAS unsigned*)(lds + (bufoff) + ldsw + _i * 8192), 16, 0, 0); } while (0)
; #define PG8_LDA(dst, b, h) do { _Pragma("unroll") for (int m = 0; m < 4; ++m) _Pragma("unroll") for (int k = 0; k < 2; ++k) dst[m][k] = *(const PG8_LAS bf16x8*)(lds + PG8_SA(b, h) + aoff + m * 2048 + k * 1024); } while (0)
; #define PG8_MMA(ai, bj, At, Bt) do { __builtin_amdgcn_s_setprio(1); _Pragma("unroll") for (int m = 0; m < 4; ++m) _Pragma("unroll") for (int n = 0; n < 2; ++n) _Pragma("unroll") for (int k = 0; k < 2; ++k) \
;         acc[ai][bj][m][n] = mma16<F16>(Bt[n][k], At[m][k], acc[ai][bj][m][n]); __builtin_amdgcn_s_setprio(0); } while (0)
; #define PG8_WAIT_V(n) asm volatile("s_waitcnt vmcnt(" #n ")" ::: "memory")
; #define PG8_WAIT_L(n) asm volatile("s_waitcnt lgkmcnt(" #n ")" ::: "memory")
; #define PG8_BAR __builtin_amdgcn_s_barrier()
; #define PG8_SCHED __builtin_amdgcn_sched_barrier(0)
; template <class Epi, class Sched, bool ALIGN_EPI = false, bool SP2 = false, bool F16 = false, bool TOKPERM = false>
; __device__ __forceinline__ void gemm_phase(PG8_LAS unsigned char* lds, const Gemm g, const Sched& S, const Epi& E, int wv) {
;     ...
;         for (int t = 0; t < nt; t += 2) {
;             const bool last = (t == nt - 2);
;             const char* a1 = cA + (size_t)(t + 1) * kstep;
;             const char* a2 = last ? nA : cA + (size_t)(t + 2) * kstep; const char* b2 = last ? nB : cB + (size_t)(t + 2) * kstep;
;             const char* a3 = a2 + kstep; const char* b3 = b2 + kstep;
;     ...
;             PG8_LDA(At, 1, 1); PG8_STAGE(PG8_SB(1, 0), b3, voffB); PG8_STAGE(PG8_SB(1, 1), b3 + hstep, voffB); PG8_STAGE(PG8_SA(1, 0), a3, voffA);
;             PG8_WAIT_V(8); PG8_WAIT_L(0); PG8_BAR; PG8_MMA(1, 0, At, B0); PG8_MMA(1, 1, At, B1); PG8_BAR; PG8_SCHED;
	s_mov_b32 m0, s94
	v_lshl_add_u64 v[236:237], v[236:237], 0, s[64:65]
	s_add_u32 s10, s14, 0x40080
	ds_read_b128 v[178:181], v187 offset:49152
	ds_read_b128 v[182:185], v187 offset:50176
	ds_read_b128 v[210:213], v187 offset:51200
	ds_read_b128 v[214:217], v187 offset:52224
	ds_read_b128 v[218:221], v187 offset:53248
	ds_read_b128 v[222:225], v187 offset:54272
	ds_read_b128 v[228:231], v187 offset:55296
	ds_read_b128 v[232:235], v187 offset:56320
	global_load_lds_dwordx4 v[236:237], off
	v_lshl_add_u64 v[236:237], v[238:239], 0, s[64:65]
	s_mov_b32 m0, s97
	s_addc_u32 s11, s15, 0
	global_load_lds_dwordx4 v[236:237], off
	v_lshl_add_u64 v[236:237], s[10:11], 0, v[138:139]
	s_mov_b32 m0, s73
	s_nop 0
	global_load_lds_dwordx4 v[236:237], off
	v_lshl_add_u64 v[236:237], s[10:11], 0, v[142:143]
	s_mov_b32 m0, s75
	s_nop 0
	global_load_lds_dwordx4 v[236:237], off
	v_lshl_add_u64 v[236:237], v[240:241], 0, s[64:65]
	s_mov_b32 m0, s4
	s_nop 0
	global_load_lds_dwordx4 v[236:237], off
	v_lshl_add_u64 v[236:237], v[242:243], 0, s[64:65]
	s_mov_b32 m0, s71
	s_nop 0
	global_load_lds_dwordx4 v[236:237], off
	s_waitcnt vmcnt(8)
	s_waitcnt lgkmcnt(0)
	s_barrier
	s_setprio 1
	s_waitcnt lgkmcnt(0)
	v_mfma_f32_16x16x32_f16 v[60:63], v[128:131], v[178:181], v[60:63]
	v_mfma_f32_16x16x32_f16 v[44:47], v[154:157], v[178:181], v[44:47]
	v_mfma_f32_16x16x32_f16 v[56:59], v[128:131], v[210:213], v[56:59]
	v_mfma_f32_16x16x32_f16 v[40:43], v[154:157], v[210:213], v[40:43]
	v_mfma_f32_16x16x32_f16 v[52:55], v[128:131], v[218:221], v[52:55]
	v_mfma_f32_16x16x32_f16 v[36:39], v[154:157], v[218:221], v[36:39]
	v_mfma_f32_16x16x32_f16 v[48:51], v[128:131], v[228:231], v[48:51]
	v_mfma_f32_16x16x32_f16 v[32:35], v[154:157], v[228:231], v[32:35]
	v_mfma_f32_16x16x32_f16 v[60:63], v[132:135], v[182:185], v[60:63]
	v_mfma_f32_16x16x32_f16 v[44:47], v[158:161], v[182:185], v[44:47]
	v_mfma_f32_16x16x32_f16 v[56:59], v[132:135], v[214:217], v[56:59]
	v_mfma_f32_16x16x32_f16 v[40:43], v[158:161], v[214:217], v[40:43]
	v_mfma_f32_16x16x32_f16 v[52:55], v[132:135], v[222:225], v[52:55]
	v_mfma_f32_16x16x32_f16 v[36:39], v[158:161], v[222:225], v[36:39]
	v_mfma_f32_16x16x32_f16 v[48:51], v[132:135], v[232:235], v[48:51]
	v_mfma_f32_16x16x32_f16 v[32:35], v[158:161], v[232:235], v[32:35]
	s_setprio 0
	s_setprio 1
	v_mfma_f32_16x16x32_f16 v[28:31], v[162:165], v[178:181], v[28:31]
	v_mfma_f32_16x16x32_f16 v[12:15], v[170:173], v[178:181], v[12:15]
	v_mfma_f32_16x16x32_f16 v[24:27], v[162:165], v[210:213], v[24:27]
	v_mfma_f32_16x16x32_f16 v[8:11], v[170:173], v[210:213], v[8:11]
	v_mfma_f32_16x16x32_f16 v[20:23], v[162:165], v[218:221], v[20:23]
	v_mfma_f32_16x16x32_f16 v[4:7], v[170:173], v[218:221], v[4:7]
	v_mfma_f32_16x16x32_f16 v[16:19], v[162:165], v[228:231], v[16:19]
	v_mfma_f32_16x16x32_f16 v[0:3], v[170:173], v[228:231], v[0:3]
	v_mfma_f32_16x16x32_f16 v[28:31], v[166:169], v[182:185], v[28:31]
	v_mfma_f32_16x16x32_f16 v[12:15], v[174:177], v[182:185], v[12:15]
	v_mfma_f32_16x16x32_f16 v[24:27], v[166:169], v[214:217], v[24:27]
	v_mfma_f32_16x16x32_f16 v[8:11], v[174:177], v[214:217], v[8:11]
	v_mfma_f32_16x16x32_f16 v[20:23], v[166:169], v[222:225], v[20:23]
	v_mfma_f32_16x16x32_f16 v[4:7], v[174:177], v[222:225], v[4:7]
	v_mfma_f32_16x16x32_f16 v[16:19], v[166:169], v[232:235], v[16:19]
	v_mfma_f32_16x16x32_f16 v[0:3], v[174:177], v[232:235], v[0:3]
	s_setprio 0
	s_barrier
	s_add_i32 s63, s63, 2
	s_add_u32 s59, s59, 0x100
	s_addc_u32 s62, s62, 0
	s_cmp_gt_u32 s63, 13
	s_mov_b64 s[10:11], s[12:13]

; #define PG8_STAGE(bufoff, gbase, voff) do { _Pragma("unroll") for (int _i = 0; _i < 2; ++_i) \
;         __builtin_amdgcn_global_load_lds((const unsigned*)((const char*)(gbase) + (voff)[_i]), (PG8_LAS unsigned*)(lds + (bufoff) + ldsw + _i * 8192), 16, 0, 0); } while (0)
; #define PG8_LDA(dst, b, h) do { _Pragma("unroll") for (int m = 0; m < 4; ++m) _Pragma("unroll") for (int k = 0; k < 2; ++k) dst[m][k] = *(const PG8_LAS bf16x8*)(lds + PG8_SA(b, h) + aoff + m * 2048 + k * 1024); } while (0)
; #define PG8_LDB(dst, b, h) do { _Pragma("unroll") for (int n = 0; n < 2; ++n) _Pragma("unroll") for (int k = 0; k < 2; ++k) dst[n][k] = *(const PG8_LAS bf16x8*)(lds + PG8_SB(b, h) + boff + n * 2048 + k * 1024); } while (0)
; #define PG8_WAIT_V(n) asm volatile("s_waitcnt vmcnt(" #n ")" ::: "memory")
; #define PG8_WAIT_L(n) asm volatile("s_waitcnt lgkmcnt(" #n ")" ::: "memory")
; #define PG8_BAR __builtin_amdgcn_s_barrier()
; #define PG8_SCHED __builtin_amdgcn_sched_barrier(0)
; template <class Epi, class Sched, bool ALIGN_EPI = false, bool SP2 = false, bool F16 = false, bool TOKPERM = false>
; __device__ __forceinline__ void gemm_phase(PG8_LAS unsigned char* lds, const Gemm g, const Sched& S, const Epi& E, int wv) {
;     ...
;         const bool has_next = S.next(ui + 1, nxt);
;         const char* nA = has_next ? (const char*)g.A + (size_t)nxt.pm * tstep : cA; const char* nB = has_next ? (const char*)g.Bt + (size_t)nxt.pn * tstep : cB;
;         for (int t = 0; t < nt; t += 2) {
;             const bool last = (t == nt - 2);
;             const char* a1 = cA + (size_t)(t + 1) * kstep;
;             const char* a2 = last ? nA : cA + (size_t)(t + 2) * kstep; const char* b2 = last ? nB : cB + (size_t)(t + 2) * kstep;
;             const char* a3 = a2 + kstep; const char* b3 = b2 + kstep;
;             if (last && has_next) S.a_ready(nxt);
;             if constexpr (SP2) {
;             PG8_LDB(B0, 0, 0); PG8_LDB(B1, 0, 1); PG8_SCHED; PG8_LDA(At, 0, 0); PG8_STAGE(PG8_SA(1, 1), a1 + hstep, voffA);
;             PG8_WAIT_V(8); PG8_WAIT_L(0); PG8_BAR; PG8_MMA(0, 0, At, B0); PG8_MMA(0, 1, At, B1); PG8_BAR; PG8_SCHED;
;             PG8_LDA(At, 0, 1); PG8_STAGE(PG8_SB(0, 0), b2, voffB); PG8_STAGE(PG8_SB(0, 1), b2 + hstep, voffB); PG8_STAGE(PG8_SA(0, 0), a2, voffA);
;             PG8_WAIT_V(8); PG8_WAIT_L(0); PG8_BAR; PG8_MMA(1, 0, At, B0); PG8_MMA(1, 1, At, B1); PG8_BAR; PG8_SCHED;
.LBB0_1606:
	s_ashr_i32 s25, s24, 31
	s_lshl_b64 s[36:37], s[24:25], 19
	s_add_u32 s36, s40, s36
	s_addc_u32 s37, s41, s37
	s_and_b64 s[42:43], s[4:5], exec
	s_cselect_b32 s25, s37, s9
	s_cselect_b32 s64, s36, s8
	s_ashr_i32 s23, s22, 31
	s_lshl_b64 s[42:43], s[22:23], 19
	s_add_u32 s42, s0, s42
	s_addc_u32 s43, s1, s43
	s_and_b64 s[44:45], s[4:5], exec
	s_cselect_b32 s23, s43, s11
	s_cselect_b32 s65, s42, s10
	s_add_u32 s8, s8, 0x40080
	s_addc_u32 s9, s9, 0
	s_add_u32 s66, s10, 0x100
	s_addc_u32 s67, s11, 0
	s_mov_b32 s68, -2
	ds_read_b128 v[172:175], v155
	ds_read_b128 v[176:179], v156
	ds_read_b128 v[180:183], v157
	ds_read_b128 v[184:187], v158
	ds_read_b128 v[188:191], v159
	ds_read_b128 v[192:195], v160
	ds_read_b128 v[196:199], v161
	ds_read_b128 v[200:203], v162
	s_add_u32 s10, s8, 0xfffc0080
	s_addc_u32 s11, s9, -1
	s_cmp_eq_u32 s68, 12
	s_cselect_b32 s45, s25, s11
	s_cselect_b32 s44, s64, s10
	s_cselect_b32 s11, s23, s67
	s_cselect_b32 s10, s65, s66
	s_mov_b32 m0, s60
	v_lshl_add_u64 v[148:149], s[8:9], 0, v[140:141]
	ds_read_b128 v[204:207], v153
	ds_read_b128 v[208:211], v153 offset:1024
	ds_read_b128 v[212:215], v153 offset:2048
	ds_read_b128 v[216:219], v153 offset:3072
	ds_read_b128 v[220:223], v153 offset:4096
	ds_read_b128 v[224:227], v153 offset:5120
	ds_read_b128 v[228:231], v153 offset:6144
	ds_read_b128 v[232:235], v153 offset:7168
	global_load_lds_dwordx4 v[148:149], off
	v_lshl_add_u64 v[148:149], s[8:9], 0, v[142:143]
	s_mov_b32 m0, s61
	s_nop 0
	global_load_lds_dwordx4 v[148:149], off
	s_waitcnt vmcnt(8)
	s_waitcnt lgkmcnt(0)
	s_barrier
	s_setprio 1
	s_waitcnt lgkmcnt(0)
	v_mfma_f32_16x16x32_f16 v[124:127], v[172:175], v[204:207], 0
	v_mfma_f32_16x16x32_f16 v[116:119], v[180:183], v[204:207], 0
	v_mfma_f32_16x16x32_f16 v[108:111], v[172:175], v[212:215], 0
	v_mfma_f32_16x16x32_f16 v[104:107], v[180:183], v[212:215], 0
	v_mfma_f32_16x16x32_f16 v[92:95], v[172:175], v[220:223], 0
	v_mfma_f32_16x16x32_f16 v[88:91], v[180:183], v[220:223], 0
	v_mfma_f32_16x16x32_f16 v[76:79], v[172:175], v[228:231], 0
	v_mfma_f32_16x16x32_f16 v[72:75], v[180:183], v[228:231], 0
	v_mfma_f32_16x16x32_f16 v[124:127], v[176:179], v[208:211], v[124:127]
	v_mfma_f32_16x16x32_f16 v[116:119], v[184:187], v[208:211], v[116:119]
	v_mfma_f32_16x16x32_f16 v[108:111], v[176:179], v[216:219], v[108:111]
	v_mfma_f32_16x16x32_f16 v[104:107], v[184:187], v[216:219], v[104:107]
	v_mfma_f32_16x16x32_f16 v[92:95], v[176:179], v[224:227], v[92:95]
	v_mfma_f32_16x16x32_f16 v[88:91], v[184:187], v[224:227], v[88:91]
	v_mfma_f32_16x16x32_f16 v[76:79], v[176:179], v[232:235], v[76:79]
	v_mfma_f32_16x16x32_f16 v[72:75], v[184:187], v[232:235], v[72:75]
	s_setprio 0
	s_setprio 1
	v_mfma_f32_16x16x32_f16 v[120:123], v[188:191], v[204:207], 0
	v_mfma_f32_16x16x32_f16 v[112:115], v[196:199], v[204:207], 0
	v_mfma_f32_16x16x32_f16 v[100:103], v[188:191], v[212:215], 0
	v_mfma_f32_16x16x32_f16 v[96:99], v[196:199], v[212:215], 0
	v_mfma_f32_16x16x32_f16 v[84:87], v[188:191], v[220:223], 0
	v_mfma_f32_16x16x32_f16 v[80:83], v[196:199], v[220:223], 0
	v_mfma_f32_16x16x32_f16 v[68:71], v[188:191], v[228:231], 0
	v_mfma_f32_16x16x32_f16 v[64:67], v[196:199], v[228:231], 0
	v_mfma_f32_16x16x32_f16 v[120:123], v[192:195], v[208:211], v[120:123]
	v_mfma_f32_16x16x32_f16 v[112:115], v[200:203], v[208:211], v[112:115]
	v_mfma_f32_16x16x32_f16 v[100:103], v[192:195], v[216:219], v[100:103]
	v_mfma_f32_16x16x32_f16 v[96:99], v[200:203], v[216:219], v[96:99]
	v_mfma_f32_16x16x32_f16 v[84:87], v[192:195], v[224:227], v[84:87]
	v_mfma_f32_16x16x32_f16 v[80:83], v[200:203], v[224:227], v[80:83]
	v_mfma_f32_16x16x32_f16 v[68:71], v[192:195], v[232:235], v[68:71]
	v_mfma_f32_16x16x32_f16 v[64:67], v[200:203], v[232:235], v[64:67]
	s_setprio 0
	s_barrier
	s_mov_b32 m0, s21
	v_lshl_add_u64 v[148:149], s[10:11], 0, v[132:133]
	s_add_u32 s70, s10, 0x40000
	ds_read_b128 v[204:207], v153 offset:16384
	ds_read_b128 v[208:211], v153 offset:17408
	ds_read_b128 v[212:215], v153 offset:18432
	ds_read_b128 v[216:219], v153 offset:19456
	ds_read_b128 v[220:223], v153 offset:20480
	ds_read_b128 v[224:227], v153 offset:21504
	ds_read_b128 v[228:231], v153 offset:22528
	ds_read_b128 v[232:235], v153 offset:23552
	global_load_lds_dwordx4 v[148:149], off
	v_lshl_add_u64 v[236:237], s[10:11], 0, v[128:129]
	s_mov_b32 m0, s33
	s_addc_u32 s71, s11, 0
	global_load_lds_dwordx4 v[236:237], off
	v_lshl_add_u64 v[238:239], s[70:71], 0, v[132:133]
	s_mov_b32 m0, s46
	v_lshl_add_u64 v[240:241], s[44:45], 0, v[130:131]
	global_load_lds_dwordx4 v[238:239], off
	v_lshl_add_u64 v[238:239], s[70:71], 0, v[128:129]
	s_mov_b32 m0, s47
	s_nop 0
	global_load_lds_dwordx4 v[238:239], off
	v_lshl_add_u64 v[238:239], s[44:45], 0, v[134:135]
	s_mov_b32 m0, s2
	s_nop 0
	global_load_lds_dwordx4 v[238:239], off
	s_mov_b32 m0, s48
	s_nop 0
	global_load_lds_dwordx4 v[240:241], off
	s_waitcnt vmcnt(8)
	s_waitcnt lgkmcnt(0)
	s_barrier
; #define PG8_STAGE(bufoff, gbase, voff) do { _Pragma("unroll") for (int _i = 0; _i < 2; ++_i) \
;         __builtin_amdgcn_global_load_lds((const unsigned*)((const char*)(gbase) + (voff)[_i]), (PG8_LAS unsigned*)(lds + (bufoff) + ldsw + _i * 8192), 16, 0, 0); } while (0)
; #define PG8_LDA(dst, b, h) do { _Pragma("unroll") for (int m = 0; m < 4; ++m) _Pragma("unroll") for (int k = 0; k < 2; ++k) dst[m][k] = *(const PG8_LAS bf16x8*)(lds + PG8_SA(b, h) + aoff + m * 2048 + k * 1024); } while (0)
; #define PG8_LDB(dst, b, h) do { _Pragma("unroll") for (int n = 0; n < 2; ++n) _Pragma("unroll") for (int k = 0; k < 2; ++k) dst[n][k] = *(const PG8_LAS bf16x8*)(lds + PG8_SB(b, h) + boff + n * 2048 + k * 1024); } while (0)
; #define PG8_MMA(ai, bj, At, Bt) do { __builtin_amdgcn_s_setprio(1); _Pragma("unroll") for (int m = 0; m < 4; ++m) _Pragma("unroll") for (int n = 0; n < 2; ++n) _Pragma("unroll") for (int k = 0; k < 2; ++k) \
;         acc[ai][bj][m][n] = mma16<F16>(Bt[n][k], At[m][k], acc[ai][bj][m][n]); __builtin_amdgcn_s_setprio(0); } while (0)
; #define PG8_WAIT_V(n) asm volatile("s_waitcnt vmcnt(" #n ")" ::: "memory")
; #define PG8_WAIT_L(n) asm volatile("s_waitcnt lgkmcnt(" #n ")" ::: "memory")
; #define PG8_BAR __builtin_amdgcn_s_barrier()
; #define PG8_SCHED __builtin_amdgcn_sched_barrier(0)
; template <class Epi, class Sched, bool ALIGN_EPI = false, bool SP2 = false, bool F16 = false, bool TOKPERM = false>
; __device__ __forceinline__ void gemm_phase(PG8_LAS unsigned char* lds, const Gemm g, const Sched& S, const Epi& E, int wv) {
;     ...
;             PG8_WAIT_V(8); PG8_WAIT_L(0); PG8_BAR; PG8_MMA(1, 0, At, B0); PG8_MMA(1, 1, At, B1); PG8_BAR; PG8_SCHED;
;             PG8_LDB(B0, 1, 0); PG8_LDB(B1, 1, 1); PG8_SCHED; PG8_LDA(At, 1, 0); PG8_STAGE(PG8_SA(0, 1), a2 + hstep, voffA);
;             PG8_WAIT_V(8); PG8_WAIT_L(0); PG8_BAR; PG8_MMA(0, 0, At, B0); PG8_MMA(0, 1, At, B1); PG8_BAR; PG8_SCHED;
	s_setprio 1
	s_waitcnt lgkmcnt(0)
	v_mfma_f32_16x16x32_f16 v[60:63], v[172:175], v[204:207], 0
	v_mfma_f32_16x16x32_f16 v[56:59], v[180:183], v[204:207], 0
	v_mfma_f32_16x16x32_f16 v[44:47], v[172:175], v[212:215], 0
	v_mfma_f32_16x16x32_f16 v[40:43], v[180:183], v[212:215], 0
	v_mfma_f32_16x16x32_f16 v[28:31], v[172:175], v[220:223], 0
	v_mfma_f32_16x16x32_f16 v[24:27], v[180:183], v[220:223], 0
	v_mfma_f32_16x16x32_f16 v[12:15], v[172:175], v[228:231], 0
	v_mfma_f32_16x16x32_f16 v[8:11], v[180:183], v[228:231], 0
	v_mfma_f32_16x16x32_f16 v[60:63], v[176:179], v[208:211], v[60:63]
	v_mfma_f32_16x16x32_f16 v[56:59], v[184:187], v[208:211], v[56:59]
	v_mfma_f32_16x16x32_f16 v[44:47], v[176:179], v[216:219], v[44:47]
	v_mfma_f32_16x16x32_f16 v[40:43], v[184:187], v[216:219], v[40:43]
	v_mfma_f32_16x16x32_f16 v[28:31], v[176:179], v[224:227], v[28:31]
	v_mfma_f32_16x16x32_f16 v[24:27], v[184:187], v[224:227], v[24:27]
	v_mfma_f32_16x16x32_f16 v[12:15], v[176:179], v[232:235], v[12:15]
	v_mfma_f32_16x16x32_f16 v[8:11], v[184:187], v[232:235], v[8:11]
	s_setprio 0
	s_setprio 1
	v_mfma_f32_16x16x32_f16 v[52:55], v[188:191], v[204:207], 0
	v_mfma_f32_16x16x32_f16 v[48:51], v[196:199], v[204:207], 0
	v_mfma_f32_16x16x32_f16 v[36:39], v[188:191], v[212:215], 0
	v_mfma_f32_16x16x32_f16 v[32:35], v[196:199], v[212:215], 0
	v_mfma_f32_16x16x32_f16 v[20:23], v[188:191], v[220:223], 0
	v_mfma_f32_16x16x32_f16 v[16:19], v[196:199], v[220:223], 0
	v_mfma_f32_16x16x32_f16 v[4:7], v[188:191], v[228:231], 0
	v_mfma_f32_16x16x32_f16 v[0:3], v[196:199], v[228:231], 0
	v_mfma_f32_16x16x32_f16 v[52:55], v[192:195], v[208:211], v[52:55]
	v_mfma_f32_16x16x32_f16 v[48:51], v[200:203], v[208:211], v[48:51]
	v_mfma_f32_16x16x32_f16 v[36:39], v[192:195], v[216:219], v[36:39]
	v_mfma_f32_16x16x32_f16 v[32:35], v[200:203], v[216:219], v[32:35]
	v_mfma_f32_16x16x32_f16 v[20:23], v[192:195], v[224:227], v[20:23]
	v_mfma_f32_16x16x32_f16 v[16:19], v[200:203], v[224:227], v[16:19]
	v_mfma_f32_16x16x32_f16 v[4:7], v[192:195], v[232:235], v[4:7]
	v_mfma_f32_16x16x32_f16 v[0:3], v[200:203], v[232:235], v[0:3]
	s_setprio 0
	s_barrier
	ds_read_b128 v[172:175], v163
	ds_read_b128 v[176:179], v164
	ds_read_b128 v[180:183], v165
	ds_read_b128 v[184:187], v166
	ds_read_b128 v[188:191], v167
	ds_read_b128 v[192:195], v168
	ds_read_b128 v[196:199], v169
	ds_read_b128 v[200:203], v170
	s_add_u32 s44, s44, 0x40000
	s_addc_u32 s45, s45, 0
	s_mov_b32 m0, s49
	v_lshl_add_u64 v[242:243], s[44:45], 0, v[134:135]
	ds_read_b128 v[204:207], v153 offset:32768
	ds_read_b128 v[208:211], v153 offset:33792
	ds_read_b128 v[212:215], v153 offset:34816
	ds_read_b128 v[216:219], v153 offset:35840
	ds_read_b128 v[220:223], v153 offset:36864
	ds_read_b128 v[224:227], v153 offset:37888
	ds_read_b128 v[228:231], v153 offset:38912
	ds_read_b128 v[232:235], v153 offset:39936
	global_load_lds_dwordx4 v[242:243], off
	v_lshl_add_u64 v[242:243], s[44:45], 0, v[130:131]
	s_mov_b32 m0, s50
	s_nop 0
	global_load_lds_dwordx4 v[242:243], off
	s_waitcnt vmcnt(8)
	s_waitcnt lgkmcnt(0)
	s_barrier
	s_setprio 1
	s_waitcnt lgkmcnt(0)
	v_mfma_f32_16x16x32_f16 v[124:127], v[172:175], v[204:207], v[124:127]
	v_mfma_f32_16x16x32_f16 v[116:119], v[180:183], v[204:207], v[116:119]
	v_mfma_f32_16x16x32_f16 v[108:111], v[172:175], v[212:215], v[108:111]
	v_mfma_f32_16x16x32_f16 v[104:107], v[180:183], v[212:215], v[104:107]
	v_mfma_f32_16x16x32_f16 v[92:95], v[172:175], v[220:223], v[92:95]
	v_mfma_f32_16x16x32_f16 v[88:91], v[180:183], v[220:223], v[88:91]
	v_mfma_f32_16x16x32_f16 v[76:79], v[172:175], v[228:231], v[76:79]
	v_mfma_f32_16x16x32_f16 v[72:75], v[180:183], v[228:231], v[72:75]
	v_mfma_f32_16x16x32_f16 v[124:127], v[176:179], v[208:211], v[124:127]
	v_mfma_f32_16x16x32_f16 v[116:119], v[184:187], v[208:211], v[116:119]
	v_mfma_f32_16x16x32_f16 v[108:111], v[176:179], v[216:219], v[108:111]
	v_mfma_f32_16x16x32_f16 v[104:107], v[184:187], v[216:219], v[104:107]
	v_mfma_f32_16x16x32_f16 v[92:95], v[176:179], v[224:227], v[92:95]
	v_mfma_f32_16x16x32_f16 v[88:91], v[184:187], v[224:227], v[88:91]
	v_mfma_f32_16x16x32_f16 v[76:79], v[176:179], v[232:235], v[76:79]
	v_mfma_f32_16x16x32_f16 v[72:75], v[184:187], v[232:235], v[72:75]
	s_setprio 0
	s_setprio 1
	v_mfma_f32_16x16x32_f16 v[120:123], v[188:191], v[204:207], v[120:123]
	v_mfma_f32_16x16x32_f16 v[112:115], v[196:199], v[204:207], v[112:115]
	v_mfma_f32_16x16x32_f16 v[100:103], v[188:191], v[212:215], v[100:103]
	v_mfma_f32_16x16x32_f16 v[96:99], v[196:199], v[212:215], v[96:99]
	v_mfma_f32_16x16x32_f16 v[84:87], v[188:191], v[220:223], v[84:87]
	v_mfma_f32_16x16x32_f16 v[80:83], v[196:199], v[220:223], v[80:83]
	v_mfma_f32_16x16x32_f16 v[68:71], v[188:191], v[228:231], v[68:71]
	v_mfma_f32_16x16x32_f16 v[64:67], v[196:199], v[228:231], v[64:67]
	v_mfma_f32_16x16x32_f16 v[120:123], v[192:195], v[208:211], v[120:123]
	v_mfma_f32_16x16x32_f16 v[112:115], v[200:203], v[208:211], v[112:115]
	v_mfma_f32_16x16x32_f16 v[100:103], v[192:195], v[216:219], v[100:103]
	v_mfma_f32_16x16x32_f16 v[96:99], v[200:203], v[216:219], v[96:99]
	v_mfma_f32_16x16x32_f16 v[84:87], v[192:195], v[224:227], v[84:87]
	v_mfma_f32_16x16x32_f16 v[80:83], v[200:203], v[224:227], v[80:83]
	v_mfma_f32_16x16x32_f16 v[68:71], v[192:195], v[232:235], v[68:71]
	v_mfma_f32_16x16x32_f16 v[64:67], v[200:203], v[232:235], v[64:67]
	s_setprio 0
	s_barrier
; #define PG8_STAGE(bufoff, gbase, voff) do { _Pragma("unroll") for (int _i = 0; _i < 2; ++_i) \
;         __builtin_amdgcn_global_load_lds((const unsigned*)((const char*)(gbase) + (voff)[_i]), (PG8_LAS unsigned*)(lds + (bufoff) + ldsw + _i * 8192), 16, 0, 0); } while (0)
; #define PG8_LDA(dst, b, h) do { _Pragma("unroll") for (int m = 0; m < 4; ++m) _Pragma("unroll") for (int k = 0; k < 2; ++k) dst[m][k] = *(const PG8_LAS bf16x8*)(lds + PG8_SA(b, h) + aoff + m * 2048 + k * 1024); } while (0)
; #define PG8_MMA(ai, bj, At, Bt) do { __builtin_amdgcn_s_setprio(1); _Pragma("unroll") for (int m = 0; m < 4; ++m) _Pragma("unroll") for (int n = 0; n < 2; ++n) _Pragma("unroll") for (int k = 0; k < 2; ++k) \
;         acc[ai][bj][m][n] = mma16<F16>(Bt[n][k], At[m][k], acc[ai][bj][m][n]); __builtin_amdgcn_s_setprio(0); } while (0)
; #define PG8_WAIT_V(n) asm volatile("s_waitcnt vmcnt(" #n ")" ::: "memory")
; #define PG8_WAIT_L(n) asm volatile("s_waitcnt lgkmcnt(" #n ")" ::: "memory")
; #define PG8_BAR __builtin_amdgcn_s_barrier()
; #define PG8_SCHED __builtin_amdgcn_sched_barrier(0)
; template <class Epi, class Sched, bool ALIGN_EPI = false, bool SP2 = false, bool F16 = false, bool TOKPERM = false>
; __device__ __forceinline__ void gemm_phase(PG8_LAS unsigned char* lds, const Gemm g, const Sched& S, const Epi& E, int wv) {
;     ...
;         for (int t = 0; t < nt; t += 2) {
;             const bool last = (t == nt - 2);
;             const char* a1 = cA + (size_t)(t + 1) * kstep;
;             const char* a2 = last ? nA : cA + (size_t)(t + 2) * kstep; const char* b2 = last ? nB : cB + (size_t)(t + 2) * kstep;
;             const char* a3 = a2 + kstep; const char* b3 = b2 + kstep;
;     ...
;             PG8_LDA(At, 1, 1); PG8_STAGE(PG8_SB(1, 0), b3, voffB); PG8_STAGE(PG8_SB(1, 1), b3 + hstep, voffB); PG8_STAGE(PG8_SA(1, 0), a3, voffA);
;             PG8_WAIT_V(8); PG8_WAIT_L(0); PG8_BAR; PG8_MMA(1, 0, At, B0); PG8_MMA(1, 1, At, B1); PG8_BAR; PG8_SCHED;
	s_mov_b32 m0, s52
	v_lshl_add_u64 v[148:149], v[148:149], 0, s[14:15]
	s_add_u32 s10, s10, 0x40080
	ds_read_b128 v[204:207], v153 offset:49152
	ds_read_b128 v[208:211], v153 offset:50176
	ds_read_b128 v[212:215], v153 offset:51200
	ds_read_b128 v[216:219], v153 offset:52224
	ds_read_b128 v[220:223], v153 offset:53248
	ds_read_b128 v[224:227], v153 offset:54272
	ds_read_b128 v[228:231], v153 offset:55296
	ds_read_b128 v[232:235], v153 offset:56320
	global_load_lds_dwordx4 v[148:149], off
	v_lshl_add_u64 v[148:149], v[236:237], 0, s[14:15]
	s_mov_b32 m0, s53
	s_addc_u32 s11, s11, 0
	global_load_lds_dwordx4 v[148:149], off
	v_lshl_add_u64 v[148:149], s[10:11], 0, v[132:133]
	s_mov_b32 m0, s56
	s_nop 0
	global_load_lds_dwordx4 v[148:149], off
	v_lshl_add_u64 v[148:149], s[10:11], 0, v[128:129]
	s_mov_b32 m0, s57
	s_nop 0
	global_load_lds_dwordx4 v[148:149], off
	v_lshl_add_u64 v[148:149], v[238:239], 0, s[14:15]
	s_mov_b32 m0, s54
	s_nop 0
	global_load_lds_dwordx4 v[148:149], off
	v_lshl_add_u64 v[148:149], v[240:241], 0, s[14:15]
	s_mov_b32 m0, s55
	s_nop 0
	global_load_lds_dwordx4 v[148:149], off
	s_waitcnt vmcnt(8)
	s_waitcnt lgkmcnt(0)
	s_barrier
	s_setprio 1
	s_waitcnt lgkmcnt(0)
	v_mfma_f32_16x16x32_f16 v[60:63], v[172:175], v[204:207], v[60:63]
	v_mfma_f32_16x16x32_f16 v[56:59], v[180:183], v[204:207], v[56:59]
	v_mfma_f32_16x16x32_f16 v[44:47], v[172:175], v[212:215], v[44:47]
	v_mfma_f32_16x16x32_f16 v[40:43], v[180:183], v[212:215], v[40:43]
	v_mfma_f32_16x16x32_f16 v[28:31], v[172:175], v[220:223], v[28:31]
	v_mfma_f32_16x16x32_f16 v[24:27], v[180:183], v[220:223], v[24:27]
	v_mfma_f32_16x16x32_f16 v[12:15], v[172:175], v[228:231], v[12:15]
	v_mfma_f32_16x16x32_f16 v[8:11], v[180:183], v[228:231], v[8:11]
	v_mfma_f32_16x16x32_f16 v[60:63], v[176:179], v[208:211], v[60:63]
	v_mfma_f32_16x16x32_f16 v[56:59], v[184:187], v[208:211], v[56:59]
	v_mfma_f32_16x16x32_f16 v[44:47], v[176:179], v[216:219], v[44:47]
	v_mfma_f32_16x16x32_f16 v[40:43], v[184:187], v[216:219], v[40:43]
	v_mfma_f32_16x16x32_f16 v[28:31], v[176:179], v[224:227], v[28:31]
	v_mfma_f32_16x16x32_f16 v[24:27], v[184:187], v[224:227], v[24:27]
	v_mfma_f32_16x16x32_f16 v[12:15], v[176:179], v[232:235], v[12:15]
	v_mfma_f32_16x16x32_f16 v[8:11], v[184:187], v[232:235], v[8:11]
	s_setprio 0
	s_setprio 1
	v_mfma_f32_16x16x32_f16 v[52:55], v[188:191], v[204:207], v[52:55]
	v_mfma_f32_16x16x32_f16 v[48:51], v[196:199], v[204:207], v[48:51]
	v_mfma_f32_16x16x32_f16 v[36:39], v[188:191], v[212:215], v[36:39]
	v_mfma_f32_16x16x32_f16 v[32:35], v[196:199], v[212:215], v[32:35]
	v_mfma_f32_16x16x32_f16 v[20:23], v[188:191], v[220:223], v[20:23]
	v_mfma_f32_16x16x32_f16 v[16:19], v[196:199], v[220:223], v[16:19]
	v_mfma_f32_16x16x32_f16 v[4:7], v[188:191], v[228:231], v[4:7]
	v_mfma_f32_16x16x32_f16 v[0:3], v[196:199], v[228:231], v[0:3]
	v_mfma_f32_16x16x32_f16 v[52:55], v[192:195], v[208:211], v[52:55]
	v_mfma_f32_16x16x32_f16 v[48:51], v[200:203], v[208:211], v[48:51]
	v_mfma_f32_16x16x32_f16 v[36:39], v[192:195], v[216:219], v[36:39]
	v_mfma_f32_16x16x32_f16 v[32:35], v[200:203], v[216:219], v[32:35]
	v_mfma_f32_16x16x32_f16 v[20:23], v[192:195], v[224:227], v[20:23]
	v_mfma_f32_16x16x32_f16 v[16:19], v[200:203], v[224:227], v[16:19]
	v_mfma_f32_16x16x32_f16 v[4:7], v[192:195], v[232:235], v[4:7]
	v_mfma_f32_16x16x32_f16 v[0:3], v[200:203], v[232:235], v[0:3]
	s_setprio 0
	s_barrier
	s_add_i32 s68, s68, 2
	s_add_u32 s8, s8, 0x100
	s_addc_u32 s9, s9, 0
	s_add_u32 s66, s66, 0x100
	s_addc_u32 s67, s67, 0
	s_cmp_gt_u32 s68, 13
